# v19 + the six steady GEMM K-loop heads aligned to a 64-byte instruction-cache line (.p2align 6)
# speedup vs baseline: 1.0113x; 1.0015x over previous
; #define PG8_STAGE(bufoff, gbase, voff) do { _Pragma("unroll") for (int _i = 0; _i < 2; ++_i) \
;         __builtin_amdgcn_global_load_lds((const unsigned*)((const char*)(gbase) + (voff)[_i]), (PG8_LAS unsigned*)(lds + (bufoff) + ldsw + _i * 8192), 16, 0, 0); } while (0)
; #define PG8_LDA(dst, b, h) do { _Pragma("unroll") for (int m = 0; m < 4; ++m) _Pragma("unroll") for (int k = 0; k < 2; ++k) dst[m][k] = *(const PG8_LAS bf16x8*)(lds + PG8_SA(b, h) + aoff + m * 2048 + k * 1024); } while (0)
; #define PG8_LDB(dst, b, h) do { _Pragma("unroll") for (int n = 0; n < 2; ++n) _Pragma("unroll") for (int k = 0; k < 2; ++k) dst[n][k] = *(const PG8_LAS bf16x8*)(lds + PG8_SB(b, h) + boff + n * 2048 + k * 1024); } while (0)
; #define PG8_WAIT_V(n) asm volatile("s_waitcnt vmcnt(" #n ")" ::: "memory")
; #define PG8_WAIT_L(n) asm volatile("s_waitcnt lgkmcnt(" #n ")" ::: "memory")
; template <class Epi, class Sched, bool ALIGN_EPI = false>
; __device__ __forceinline__ void gemm_phase8(PG8_LAS unsigned char* lds, const Gemm g, const Sched& S, const Epi& E) {
;     ...
;         const bool has_next = S.next(ui + 1, nxt);
;         const size_t nko = (has_next && nxt.kp > 0) ? (size_t)nxt.kp * g.kpiece : 0;
;         const char* nA = has_next ? (const char*)g.A + (size_t)nxt.pm * tstepA + (size_t)nxt.pn * astep + nko : cA; const char* nB = has_next ? (const char*)g.Bt + (size_t)nxt.pn * tstepB + nko : cB;
;         const int nt = (cur.kp < 0 ? g.K : g.kpiece) / 128;
;         for (int t = 0; t < nt; t += 2) {
;             const bool last = (t == nt - 2);
;             const char* a1 = cA + (size_t)(t + 1) * kstep;
;             const char* a2 = last ? nA : cA + (size_t)(t + 2) * kstep; const char* b2 = last ? nB : cB + (size_t)(t + 2) * kstep;
;             const char* a3 = a2 + kstep; const char* b3 = b2 + kstep;
;             if (last && has_next) S.a_ready(nxt);
;             PG8_LDB(B0, 0, 0); PG8_LDB(B1, 0, 1); PG8_SCHED; PG8_LDA(At, 0, 0); PG8_STAGE(PG8_SA(1, 1), a1 + hstepA, voffA);
;             PG8_WAIT_V(8); PG8_WAIT_L(0); PG8_BAR; PG8_MMA(0, 0, At, B0); PG8_MMA(0, 1, At, B1); PG8_BAR; PG8_SCHED;
;             PG8_LDA(At, 0, 1); PG8_STAGE(PG8_SB(0, 0), b2, voffB); PG8_STAGE(PG8_SB(0, 1), b2 + hstepB, voffB); PG8_STAGE(PG8_SA(0, 0), a2, voffA);
;             PG8_WAIT_V(8); PG8_WAIT_L(0); PG8_BAR; PG8_MMA(1, 0, At, B0); PG8_MMA(1, 1, At, B1); PG8_BAR; PG8_SCHED;
.LBB0_324:
	s_ashr_i32 s15, s14, 31
	s_lshl_b64 s[16:17], s[14:15], 19
	s_add_u32 s16, s28, s16
	s_addc_u32 s17, s29, s17
	s_and_b64 s[18:19], s[2:3], exec
	s_cselect_b32 s15, s17, s23
	s_cselect_b32 s61, s16, s22
	s_ashr_i32 s13, s12, 31
	s_lshl_b64 s[18:19], s[12:13], 19
	s_add_u32 s18, s4, s18
	s_addc_u32 s19, s5, s19
	s_and_b64 s[26:27], s[2:3], exec
	s_cselect_b32 s13, s19, s25
	s_cselect_b32 s62, s18, s24
	s_add_u32 s22, s22, 0x40080
	s_addc_u32 s23, s23, 0
	s_add_u32 s63, s24, 0x100
	s_addc_u32 s64, s25, 0
	s_mov_b32 s65, -2
	ds_read_b128 v[18:21], v191
	ds_read_b128 v[26:29], v191 offset:2048
	ds_read_b128 v[22:25], v192
	ds_read_b128 v[30:33], v192 offset:2048
	ds_read_b128 v[2:5], v193
	ds_read_b128 v[10:13], v193 offset:2048
	ds_read_b128 v[6:9], v194
	ds_read_b128 v[14:17], v194 offset:2048
	s_add_u32 s24, s22, 0xfffc0080
	s_addc_u32 s25, s23, -1
	s_cmp_eq_u32 s65, 12
	s_cselect_b32 s27, s15, s25
	s_cselect_b32 s26, s61, s24
	s_cselect_b32 s25, s13, s64
	s_cselect_b32 s24, s62, s63
	s_add_i32 m0, s21, 0xc000
	ds_read_b128 v[178:181], v195
	ds_read_b128 v[198:201], v195 offset:2048
	ds_read_b128 v[182:185], v196
	ds_read_b128 v[202:205], v196 offset:2048
	ds_read_b128 v[206:209], v195 offset:4096
	ds_read_b128 v[214:217], v195 offset:6144
	ds_read_b128 v[210:213], v196 offset:4096
	ds_read_b128 v[218:221], v196 offset:6144
	global_load_lds_dwordx4 v170, s[22:23]
	s_add_i32 m0, s21, 0xe000
	s_nop 0
	global_load_lds_dwordx4 v172, s[22:23]
	s_waitcnt vmcnt(8)
	s_waitcnt lgkmcnt(0)
	s_barrier
	s_setprio 1
	s_waitcnt lgkmcnt(0)
	v_mfma_scale_f32_16x16x128_f8f6f4 v[158:161], v[18:25], v[178:185], 0, v1, v186 op_sel_hi:[0,0,0]
	v_mfma_scale_f32_16x16x128_f8f6f4 v[150:153], v[26:33], v[178:185], 0, v1, v186 op_sel_hi:[0,0,0]
	v_mfma_scale_f32_16x16x128_f8f6f4 v[142:145], v[18:25], v[198:205], 0, v1, v186 op_sel_hi:[0,0,0]
	v_mfma_scale_f32_16x16x128_f8f6f4 v[134:137], v[26:33], v[198:205], 0, v1, v186 op_sel_hi:[0,0,0]
	v_mfma_scale_f32_16x16x128_f8f6f4 v[126:129], v[18:25], v[206:213], 0, v1, v186 op_sel_hi:[0,0,0]
	v_mfma_scale_f32_16x16x128_f8f6f4 v[118:121], v[26:33], v[206:213], 0, v1, v186 op_sel_hi:[0,0,0]
	v_mfma_scale_f32_16x16x128_f8f6f4 v[110:113], v[18:25], v[214:221], 0, v1, v186 op_sel_hi:[0,0,0]
	v_mfma_scale_f32_16x16x128_f8f6f4 v[102:105], v[26:33], v[214:221], 0, v1, v186 op_sel_hi:[0,0,0]
	s_setprio 0
	s_setprio 1
	v_mfma_scale_f32_16x16x128_f8f6f4 v[154:157], v[2:9], v[178:185], 0, v1, v186 op_sel_hi:[0,0,0]
	v_mfma_scale_f32_16x16x128_f8f6f4 v[146:149], v[10:17], v[178:185], 0, v1, v186 op_sel_hi:[0,0,0]
	v_mfma_scale_f32_16x16x128_f8f6f4 v[138:141], v[2:9], v[198:205], 0, v1, v186 op_sel_hi:[0,0,0]
	v_mfma_scale_f32_16x16x128_f8f6f4 v[130:133], v[10:17], v[198:205], 0, v1, v186 op_sel_hi:[0,0,0]
	v_mfma_scale_f32_16x16x128_f8f6f4 v[122:125], v[2:9], v[206:213], 0, v1, v186 op_sel_hi:[0,0,0]
	v_mfma_scale_f32_16x16x128_f8f6f4 v[114:117], v[10:17], v[206:213], 0, v1, v186 op_sel_hi:[0,0,0]
	v_mfma_scale_f32_16x16x128_f8f6f4 v[106:109], v[2:9], v[214:221], 0, v1, v186 op_sel_hi:[0,0,0]
	v_mfma_scale_f32_16x16x128_f8f6f4 v[98:101], v[10:17], v[214:221], 0, v1, v186 op_sel_hi:[0,0,0]
	s_setprio 0
	s_barrier
	s_add_i32 s66, s57, s30
	s_mov_b32 m0, s66
	ds_read_b128 v[198:201], v195 offset:16384
	ds_read_b128 v[206:209], v195 offset:18432
	ds_read_b128 v[202:205], v196 offset:16384
	ds_read_b128 v[210:213], v196 offset:18432
	ds_read_b128 v[214:217], v195 offset:20480
	ds_read_b128 v[222:225], v195 offset:22528
	ds_read_b128 v[218:221], v196 offset:20480
	ds_read_b128 v[226:229], v196 offset:22528
	global_load_lds_dwordx4 v164, s[24:25]
	s_add_i32 m0, s66, 0x2000
	s_add_u32 s66, s24, 0x40000
	s_addc_u32 s67, s25, 0
	s_add_i32 s72, s58, s30
	global_load_lds_dwordx4 v168, s[24:25]
	s_mov_b32 m0, s72
	s_nop 0
	global_load_lds_dwordx4 v164, s[66:67]
	s_add_i32 m0, s72, 0x2000
	s_nop 0
	global_load_lds_dwordx4 v168, s[66:67]
	s_mov_b32 m0, s21
	s_nop 0
	global_load_lds_dwordx4 v162, s[26:27]
	s_mov_b32 m0, s34
	s_nop 0
	global_load_lds_dwordx4 v166, s[26:27]
	s_waitcnt vmcnt(8)
	s_waitcnt lgkmcnt(0)
	s_barrier
	s_setprio 1
	s_waitcnt lgkmcnt(0)
	v_mfma_scale_f32_16x16x128_f8f6f4 v[94:97], v[18:25], v[198:205], 0, v1, v186 op_sel_hi:[0,0,0]
	v_mfma_scale_f32_16x16x128_f8f6f4 v[86:89], v[26:33], v[198:205], 0, v1, v186 op_sel_hi:[0,0,0]
	v_mfma_scale_f32_16x16x128_f8f6f4 v[78:81], v[18:25], v[206:213], 0, v1, v186 op_sel_hi:[0,0,0]
	v_mfma_scale_f32_16x16x128_f8f6f4 v[70:73], v[26:33], v[206:213], 0, v1, v186 op_sel_hi:[0,0,0]
	v_mfma_scale_f32_16x16x128_f8f6f4 v[62:65], v[18:25], v[214:221], 0, v1, v186 op_sel_hi:[0,0,0]
	v_mfma_scale_f32_16x16x128_f8f6f4 v[54:57], v[26:33], v[214:221], 0, v1, v186 op_sel_hi:[0,0,0]
	v_mfma_scale_f32_16x16x128_f8f6f4 v[46:49], v[18:25], v[222:229], 0, v1, v186 op_sel_hi:[0,0,0]
	v_mfma_scale_f32_16x16x128_f8f6f4 v[38:41], v[26:33], v[222:229], 0, v1, v186 op_sel_hi:[0,0,0]
	s_setprio 0
	s_setprio 1
	v_mfma_scale_f32_16x16x128_f8f6f4 v[90:93], v[2:9], v[198:205], 0, v1, v186 op_sel_hi:[0,0,0]
	v_mfma_scale_f32_16x16x128_f8f6f4 v[82:85], v[10:17], v[198:205], 0, v1, v186 op_sel_hi:[0,0,0]
	v_mfma_scale_f32_16x16x128_f8f6f4 v[74:77], v[2:9], v[206:213], 0, v1, v186 op_sel_hi:[0,0,0]
	v_mfma_scale_f32_16x16x128_f8f6f4 v[66:69], v[10:17], v[206:213], 0, v1, v186 op_sel_hi:[0,0,0]
	v_mfma_scale_f32_16x16x128_f8f6f4 v[58:61], v[2:9], v[214:221], 0, v1, v186 op_sel_hi:[0,0,0]
	v_mfma_scale_f32_16x16x128_f8f6f4 v[50:53], v[10:17], v[214:221], 0, v1, v186 op_sel_hi:[0,0,0]
	v_mfma_scale_f32_16x16x128_f8f6f4 v[42:45], v[2:9], v[222:229], 0, v1, v186 op_sel_hi:[0,0,0]
	v_mfma_scale_f32_16x16x128_f8f6f4 v[34:37], v[10:17], v[222:229], 0, v1, v186 op_sel_hi:[0,0,0]
	s_setprio 0
	s_barrier
; #define PG8_STAGE(bufoff, gbase, voff) do { _Pragma("unroll") for (int _i = 0; _i < 2; ++_i) \
;         __builtin_amdgcn_global_load_lds((const unsigned*)((const char*)(gbase) + (voff)[_i]), (PG8_LAS unsigned*)(lds + (bufoff) + ldsw + _i * 8192), 16, 0, 0); } while (0)
; #define PG8_LDA(dst, b, h) do { _Pragma("unroll") for (int m = 0; m < 4; ++m) _Pragma("unroll") for (int k = 0; k < 2; ++k) dst[m][k] = *(const PG8_LAS bf16x8*)(lds + PG8_SA(b, h) + aoff + m * 2048 + k * 1024); } while (0)
; #define PG8_LDB(dst, b, h) do { _Pragma("unroll") for (int n = 0; n < 2; ++n) _Pragma("unroll") for (int k = 0; k < 2; ++k) dst[n][k] = *(const PG8_LAS bf16x8*)(lds + PG8_SB(b, h) + boff + n * 2048 + k * 1024); } while (0)
; #define PG8_BAR __builtin_amdgcn_s_barrier()
; template <class Epi, class Sched, bool ALIGN_EPI = false>
; __device__ __forceinline__ void gemm_phase8(PG8_LAS unsigned char* lds, const Gemm g, const Sched& S, const Epi& E) {
;     ...
;         for (int t = 0; t < nt; t += 2) {
;             const bool last = (t == nt - 2);
;             const char* a1 = cA + (size_t)(t + 1) * kstep;
;             const char* a2 = last ? nA : cA + (size_t)(t + 2) * kstep; const char* b2 = last ? nB : cB + (size_t)(t + 2) * kstep;
;             const char* a3 = a2 + kstep; const char* b3 = b2 + kstep;
;             if (last && has_next) S.a_ready(nxt);
;             PG8_LDB(B0, 0, 0); PG8_LDB(B1, 0, 1); PG8_SCHED; PG8_LDA(At, 0, 0); PG8_STAGE(PG8_SA(1, 1), a1 + hstepA, voffA);
;             PG8_WAIT_V(8); PG8_WAIT_L(0); PG8_BAR; PG8_MMA(0, 0, At, B0); PG8_MMA(0, 1, At, B1); PG8_BAR; PG8_SCHED;
;             PG8_LDA(At, 0, 1); PG8_STAGE(PG8_SB(0, 0), b2, voffB); PG8_STAGE(PG8_SB(0, 1), b2 + hstepB, voffB); PG8_STAGE(PG8_SA(0, 0), a2, voffA);
;             PG8_WAIT_V(8); PG8_WAIT_L(0); PG8_BAR; PG8_MMA(1, 0, At, B0); PG8_MMA(1, 1, At, B1); PG8_BAR; PG8_SCHED;
;             PG8_LDB(B0, 1, 0); PG8_LDB(B1, 1, 1); PG8_SCHED; PG8_LDA(At, 1, 0); PG8_STAGE(PG8_SA(0, 1), a2 + hstepA, voffA);
;             PG8_WAIT_V(8); PG8_WAIT_L(0); PG8_BAR; PG8_MMA(0, 0, At, B0); PG8_MMA(0, 1, At, B1); PG8_BAR; PG8_SCHED;
;             PG8_LDA(At, 1, 1); PG8_STAGE(PG8_SB(1, 0), b3, voffB); PG8_STAGE(PG8_SB(1, 1), b3 + hstepB, voffB); PG8_STAGE(PG8_SA(1, 0), a3, voffA);
;             PG8_WAIT_V(8); PG8_WAIT_L(0); PG8_BAR; PG8_MMA(1, 0, At, B0); PG8_MMA(1, 1, At, B1); PG8_BAR; PG8_SCHED;
	s_add_i32 s66, 0, 0x18000
	s_add_i32 s67, 0, 0x1c000
	v_add_u32_e32 v6, s66, v187
	v_add_u32_e32 v14, s66, v188
	v_add_u32_e32 v22, s67, v187
	v_add_u32_e32 v30, s67, v188
	ds_read_b128 v[2:5], v6
	ds_read_b128 v[10:13], v6 offset:2048
	ds_read_b128 v[6:9], v14
	ds_read_b128 v[14:17], v14 offset:2048
	ds_read_b128 v[18:21], v22
	ds_read_b128 v[26:29], v22 offset:2048
	ds_read_b128 v[22:25], v30
	ds_read_b128 v[30:33], v30 offset:2048
	s_add_u32 s26, s26, 0x40000
	s_addc_u32 s27, s27, 0
	s_mov_b32 m0, s35
	ds_read_b128 v[198:201], v195 offset:32768
	ds_read_b128 v[206:209], v195 offset:34816
	ds_read_b128 v[202:205], v196 offset:32768
	ds_read_b128 v[210:213], v196 offset:34816
	ds_read_b128 v[214:217], v195 offset:36864
	ds_read_b128 v[222:225], v195 offset:38912
	ds_read_b128 v[218:221], v196 offset:36864
	ds_read_b128 v[226:229], v196 offset:38912
	global_load_lds_dwordx4 v162, s[26:27]
	s_mov_b32 m0, s52
	s_nop 0
	global_load_lds_dwordx4 v166, s[26:27]
	s_waitcnt vmcnt(8)
	s_waitcnt lgkmcnt(0)
	s_barrier
	s_setprio 1
	s_waitcnt lgkmcnt(0)
	v_mfma_scale_f32_16x16x128_f8f6f4 v[158:161], v[2:9], v[198:205], v[158:161], v1, v186 op_sel_hi:[0,0,0]
	v_mfma_scale_f32_16x16x128_f8f6f4 v[150:153], v[10:17], v[198:205], v[150:153], v1, v186 op_sel_hi:[0,0,0]
	v_mfma_scale_f32_16x16x128_f8f6f4 v[142:145], v[2:9], v[206:213], v[142:145], v1, v186 op_sel_hi:[0,0,0]
	v_mfma_scale_f32_16x16x128_f8f6f4 v[134:137], v[10:17], v[206:213], v[134:137], v1, v186 op_sel_hi:[0,0,0]
	v_mfma_scale_f32_16x16x128_f8f6f4 v[126:129], v[2:9], v[214:221], v[126:129], v1, v186 op_sel_hi:[0,0,0]
	v_mfma_scale_f32_16x16x128_f8f6f4 v[118:121], v[10:17], v[214:221], v[118:121], v1, v186 op_sel_hi:[0,0,0]
	v_mfma_scale_f32_16x16x128_f8f6f4 v[110:113], v[2:9], v[222:229], v[110:113], v1, v186 op_sel_hi:[0,0,0]
	v_mfma_scale_f32_16x16x128_f8f6f4 v[102:105], v[10:17], v[222:229], v[102:105], v1, v186 op_sel_hi:[0,0,0]
	s_setprio 0
	s_setprio 1
	v_mfma_scale_f32_16x16x128_f8f6f4 v[154:157], v[18:25], v[198:205], v[154:157], v1, v186 op_sel_hi:[0,0,0]
	v_mfma_scale_f32_16x16x128_f8f6f4 v[146:149], v[26:33], v[198:205], v[146:149], v1, v186 op_sel_hi:[0,0,0]
	v_mfma_scale_f32_16x16x128_f8f6f4 v[138:141], v[18:25], v[206:213], v[138:141], v1, v186 op_sel_hi:[0,0,0]
	v_mfma_scale_f32_16x16x128_f8f6f4 v[130:133], v[26:33], v[206:213], v[130:133], v1, v186 op_sel_hi:[0,0,0]
	v_mfma_scale_f32_16x16x128_f8f6f4 v[122:125], v[18:25], v[214:221], v[122:125], v1, v186 op_sel_hi:[0,0,0]
	v_mfma_scale_f32_16x16x128_f8f6f4 v[114:117], v[26:33], v[214:221], v[114:117], v1, v186 op_sel_hi:[0,0,0]
	v_mfma_scale_f32_16x16x128_f8f6f4 v[106:109], v[18:25], v[222:229], v[106:109], v1, v186 op_sel_hi:[0,0,0]
	v_mfma_scale_f32_16x16x128_f8f6f4 v[98:101], v[26:33], v[222:229], v[98:101], v1, v186 op_sel_hi:[0,0,0]
	s_setprio 0
	s_barrier
	s_add_i32 s101, s66, s30
	s_add_u32 s98, s24, s8
	s_addc_u32 s99, s25, s9
	s_mov_b32 m0, s101
	ds_read_b128 v[198:201], v195 offset:49152
	ds_read_b128 v[206:209], v195 offset:51200
	ds_read_b128 v[202:205], v196 offset:49152
	ds_read_b128 v[210:213], v196 offset:51200
	ds_read_b128 v[214:217], v195 offset:53248
	ds_read_b128 v[222:225], v195 offset:55296
	ds_read_b128 v[218:221], v196 offset:53248
	ds_read_b128 v[226:229], v196 offset:55296
	global_load_lds_dwordx4 v164, s[98:99]
	s_add_i32 m0, s101, 0x2000
	s_add_u32 s24, s24, 0x40080
	s_addc_u32 s25, s25, 0
	s_add_i32 s101, s67, s30
	global_load_lds_dwordx4 v168, s[98:99]
	s_add_u32 s98, s26, s8
	s_addc_u32 s99, s27, s9
	s_sub_u32 s98, s98, 0x40000
	s_subb_u32 s99, s99, 0
	s_mov_b32 m0, s101
	s_nop 0
	global_load_lds_dwordx4 v164, s[24:25]
	s_add_i32 m0, s101, 0x2000
	s_nop 0
	global_load_lds_dwordx4 v168, s[24:25]
	s_mov_b32 m0, s55
	s_nop 0
	global_load_lds_dwordx4 v162, s[98:99]
	s_mov_b32 m0, s56
	s_nop 0
	global_load_lds_dwordx4 v166, s[98:99]
	s_waitcnt vmcnt(8)
	s_waitcnt lgkmcnt(0)
	s_barrier
	s_setprio 1
	s_waitcnt lgkmcnt(0)
	v_mfma_scale_f32_16x16x128_f8f6f4 v[94:97], v[2:9], v[198:205], v[94:97], v1, v186 op_sel_hi:[0,0,0]
	v_mfma_scale_f32_16x16x128_f8f6f4 v[86:89], v[10:17], v[198:205], v[86:89], v1, v186 op_sel_hi:[0,0,0]
	v_mfma_scale_f32_16x16x128_f8f6f4 v[78:81], v[2:9], v[206:213], v[78:81], v1, v186 op_sel_hi:[0,0,0]
	v_mfma_scale_f32_16x16x128_f8f6f4 v[70:73], v[10:17], v[206:213], v[70:73], v1, v186 op_sel_hi:[0,0,0]
	v_mfma_scale_f32_16x16x128_f8f6f4 v[62:65], v[2:9], v[214:221], v[62:65], v1, v186 op_sel_hi:[0,0,0]
	v_mfma_scale_f32_16x16x128_f8f6f4 v[54:57], v[10:17], v[214:221], v[54:57], v1, v186 op_sel_hi:[0,0,0]
	v_mfma_scale_f32_16x16x128_f8f6f4 v[46:49], v[2:9], v[222:229], v[46:49], v1, v186 op_sel_hi:[0,0,0]
	v_mfma_scale_f32_16x16x128_f8f6f4 v[38:41], v[10:17], v[222:229], v[38:41], v1, v186 op_sel_hi:[0,0,0]
	s_setprio 0
	s_setprio 1
	v_mfma_scale_f32_16x16x128_f8f6f4 v[90:93], v[18:25], v[198:205], v[90:93], v1, v186 op_sel_hi:[0,0,0]
	v_mfma_scale_f32_16x16x128_f8f6f4 v[82:85], v[26:33], v[198:205], v[82:85], v1, v186 op_sel_hi:[0,0,0]
	v_mfma_scale_f32_16x16x128_f8f6f4 v[74:77], v[18:25], v[206:213], v[74:77], v1, v186 op_sel_hi:[0,0,0]
	v_mfma_scale_f32_16x16x128_f8f6f4 v[66:69], v[26:33], v[206:213], v[66:69], v1, v186 op_sel_hi:[0,0,0]
	v_mfma_scale_f32_16x16x128_f8f6f4 v[58:61], v[18:25], v[214:221], v[58:61], v1, v186 op_sel_hi:[0,0,0]
	v_mfma_scale_f32_16x16x128_f8f6f4 v[50:53], v[26:33], v[214:221], v[50:53], v1, v186 op_sel_hi:[0,0,0]
	v_mfma_scale_f32_16x16x128_f8f6f4 v[42:45], v[18:25], v[222:229], v[42:45], v1, v186 op_sel_hi:[0,0,0]
	v_mfma_scale_f32_16x16x128_f8f6f4 v[34:37], v[26:33], v[222:229], v[34:37], v1, v186 op_sel_hi:[0,0,0]
	s_setprio 0
	s_barrier
	s_add_i32 s65, s65, 2
	s_add_u32 s22, s22, 0x100
	s_addc_u32 s23, s23, 0
	s_add_u32 s63, s63, 0x100
	s_addc_u32 s64, s64, 0
	s_cmp_gt_u32 s65, 13
	.p2align	6

; #define PG8_STAGE(bufoff, gbase, voff) do { _Pragma("unroll") for (int _i = 0; _i < 2; ++_i) \
;         __builtin_amdgcn_global_load_lds((const unsigned*)((const char*)(gbase) + (voff)[_i]), (PG8_LAS unsigned*)(lds + (bufoff) + ldsw + _i * 8192), 16, 0, 0); } while (0)
; #define PG8_LDA(dst, b, h) do { _Pragma("unroll") for (int m = 0; m < 4; ++m) _Pragma("unroll") for (int k = 0; k < 2; ++k) dst[m][k] = *(const PG8_LAS bf16x8*)(lds + PG8_SA(b, h) + aoff + m * 2048 + k * 1024); } while (0)
; #define PG8_LDB(dst, b, h) do { _Pragma("unroll") for (int n = 0; n < 2; ++n) _Pragma("unroll") for (int k = 0; k < 2; ++k) dst[n][k] = *(const PG8_LAS bf16x8*)(lds + PG8_SB(b, h) + boff + n * 2048 + k * 1024); } while (0)
; #define PG8_WAIT_V(n) asm volatile("s_waitcnt vmcnt(" #n ")" ::: "memory")
; #define PG8_WAIT_L(n) asm volatile("s_waitcnt lgkmcnt(" #n ")" ::: "memory")
; template <class Epi, class Sched, bool ALIGN_EPI = false>
; __device__ __forceinline__ void gemm_phase8(PG8_LAS unsigned char* lds, const Gemm g, const Sched& S, const Epi& E) {
;     ...
;         const bool has_next = S.next(ui + 1, nxt);
;         const size_t nko = (has_next && nxt.kp > 0) ? (size_t)nxt.kp * g.kpiece : 0;
;         const char* nA = has_next ? (const char*)g.A + (size_t)nxt.pm * tstepA + (size_t)nxt.pn * astep + nko : cA; const char* nB = has_next ? (const char*)g.Bt + (size_t)nxt.pn * tstepB + nko : cB;
;         const int nt = (cur.kp < 0 ? g.K : g.kpiece) / 128;
;         for (int t = 0; t < nt; t += 2) {
;             const bool last = (t == nt - 2);
;             const char* a1 = cA + (size_t)(t + 1) * kstep;
;             const char* a2 = last ? nA : cA + (size_t)(t + 2) * kstep; const char* b2 = last ? nB : cB + (size_t)(t + 2) * kstep;
;             const char* a3 = a2 + kstep; const char* b3 = b2 + kstep;
;             if (last && has_next) S.a_ready(nxt);
;             PG8_LDB(B0, 0, 0); PG8_LDB(B1, 0, 1); PG8_SCHED; PG8_LDA(At, 0, 0); PG8_STAGE(PG8_SA(1, 1), a1 + hstepA, voffA);
;             PG8_WAIT_V(8); PG8_WAIT_L(0); PG8_BAR; PG8_MMA(0, 0, At, B0); PG8_MMA(0, 1, At, B1); PG8_BAR; PG8_SCHED;
;             PG8_LDA(At, 0, 1); PG8_STAGE(PG8_SB(0, 0), b2, voffB); PG8_STAGE(PG8_SB(0, 1), b2 + hstepB, voffB); PG8_STAGE(PG8_SA(0, 0), a2, voffA);
;             PG8_WAIT_V(8); PG8_WAIT_L(0); PG8_BAR; PG8_MMA(1, 0, At, B0); PG8_MMA(1, 1, At, B1); PG8_BAR; PG8_SCHED;
.LBB0_501:
	s_cmp_gt_i32 s24, -1
	s_cselect_b64 s[26:27], -1, 0
	s_cmp_lt_i32 s24, 0
	s_cselect_b32 s25, 44, 4
	s_add_i32 s81, s25, -2
	s_add_u32 s28, s28, 0xb0080
	s_addc_u32 s29, s29, 0
	s_add_u32 s82, s30, 0x100
	s_mov_b32 s34, 0
	s_addc_u32 s83, s31, 0
	ds_read_b128 v[18:21], v187
	ds_read_b128 v[26:29], v187 offset:2048
	ds_read_b128 v[22:25], v188
	ds_read_b128 v[30:33], v188 offset:2048
	ds_read_b128 v[2:5], v189
	ds_read_b128 v[10:13], v189 offset:2048
	ds_read_b128 v[6:9], v190
	ds_read_b128 v[14:17], v190 offset:2048
	s_add_i32 s84, s34, 2
	s_add_u32 s30, s28, 0xfff50080
	s_addc_u32 s31, s29, -1
	s_cmp_eq_u32 s81, s34
	s_cselect_b32 s34, s20, s30
	s_cselect_b32 s35, s21, s31
	s_cselect_b32 s31, s23, s83
	s_cselect_b32 s30, s22, s82
	s_add_i32 m0, s54, 0xc000
	ds_read_b128 v[174:177], v191
	ds_read_b128 v[194:197], v191 offset:2048
	ds_read_b128 v[178:181], v192
	ds_read_b128 v[198:201], v192 offset:2048
	ds_read_b128 v[202:205], v191 offset:4096
	ds_read_b128 v[210:213], v191 offset:6144
	ds_read_b128 v[206:209], v192 offset:4096
	ds_read_b128 v[214:217], v192 offset:6144
	global_load_lds_dwordx4 v170, s[28:29]
	s_add_i32 m0, s54, 0xe000
	s_nop 0
	global_load_lds_dwordx4 v172, s[28:29]
	s_waitcnt vmcnt(8)
	s_waitcnt lgkmcnt(0)
	s_barrier
	s_setprio 1
	s_waitcnt lgkmcnt(0)
	v_mfma_scale_f32_16x16x128_f8f6f4 v[158:161], v[18:25], v[174:181], 0, v1, v182 op_sel_hi:[0,0,0]
	v_mfma_scale_f32_16x16x128_f8f6f4 v[154:157], v[26:33], v[174:181], 0, v1, v182 op_sel_hi:[0,0,0]
	v_mfma_scale_f32_16x16x128_f8f6f4 v[142:145], v[18:25], v[194:201], 0, v1, v182 op_sel_hi:[0,0,0]
	v_mfma_scale_f32_16x16x128_f8f6f4 v[138:141], v[26:33], v[194:201], 0, v1, v182 op_sel_hi:[0,0,0]
	v_mfma_scale_f32_16x16x128_f8f6f4 v[126:129], v[18:25], v[202:209], 0, v1, v182 op_sel_hi:[0,0,0]
	v_mfma_scale_f32_16x16x128_f8f6f4 v[122:125], v[26:33], v[202:209], 0, v1, v182 op_sel_hi:[0,0,0]
	v_mfma_scale_f32_16x16x128_f8f6f4 v[110:113], v[18:25], v[210:217], 0, v1, v182 op_sel_hi:[0,0,0]
	v_mfma_scale_f32_16x16x128_f8f6f4 v[106:109], v[26:33], v[210:217], 0, v1, v182 op_sel_hi:[0,0,0]
	s_setprio 0
	s_setprio 1
	v_mfma_scale_f32_16x16x128_f8f6f4 v[150:153], v[2:9], v[174:181], 0, v1, v182 op_sel_hi:[0,0,0]
	v_mfma_scale_f32_16x16x128_f8f6f4 v[146:149], v[10:17], v[174:181], 0, v1, v182 op_sel_hi:[0,0,0]
	v_mfma_scale_f32_16x16x128_f8f6f4 v[134:137], v[2:9], v[194:201], 0, v1, v182 op_sel_hi:[0,0,0]
	v_mfma_scale_f32_16x16x128_f8f6f4 v[130:133], v[10:17], v[194:201], 0, v1, v182 op_sel_hi:[0,0,0]
	v_mfma_scale_f32_16x16x128_f8f6f4 v[118:121], v[2:9], v[202:209], 0, v1, v182 op_sel_hi:[0,0,0]
	v_mfma_scale_f32_16x16x128_f8f6f4 v[114:117], v[10:17], v[202:209], 0, v1, v182 op_sel_hi:[0,0,0]
	v_mfma_scale_f32_16x16x128_f8f6f4 v[102:105], v[2:9], v[210:217], 0, v1, v182 op_sel_hi:[0,0,0]
	v_mfma_scale_f32_16x16x128_f8f6f4 v[98:101], v[10:17], v[210:217], 0, v1, v182 op_sel_hi:[0,0,0]
	s_setprio 0
	s_barrier
	s_add_i32 s85, s65, s53
	s_mov_b32 m0, s85
	ds_read_b128 v[194:197], v191 offset:16384
	ds_read_b128 v[202:205], v191 offset:18432
	ds_read_b128 v[198:201], v192 offset:16384
	ds_read_b128 v[206:209], v192 offset:18432
	ds_read_b128 v[210:213], v191 offset:20480
	ds_read_b128 v[218:221], v191 offset:22528
	ds_read_b128 v[214:217], v192 offset:20480
	ds_read_b128 v[222:225], v192 offset:22528
	global_load_lds_dwordx4 v164, s[30:31]
	s_add_i32 m0, s85, 0x2000
	s_add_u32 s88, s30, 0xb0000
	s_addc_u32 s89, s31, 0
	s_add_i32 s85, s66, s53
	global_load_lds_dwordx4 v168, s[30:31]
	s_mov_b32 m0, s85
	s_nop 0
	global_load_lds_dwordx4 v164, s[88:89]
	s_add_i32 m0, s85, 0x2000
	s_nop 0
	global_load_lds_dwordx4 v168, s[88:89]
	s_mov_b32 m0, s54
	s_nop 0
	global_load_lds_dwordx4 v162, s[34:35]
	s_mov_b32 m0, s55
	s_nop 0
	global_load_lds_dwordx4 v166, s[34:35]
	s_waitcnt vmcnt(8)
	s_waitcnt lgkmcnt(0)
	s_barrier
	s_setprio 1
	s_waitcnt lgkmcnt(0)
	v_mfma_scale_f32_16x16x128_f8f6f4 v[94:97], v[18:25], v[194:201], 0, v1, v182 op_sel_hi:[0,0,0]
	v_mfma_scale_f32_16x16x128_f8f6f4 v[90:93], v[26:33], v[194:201], 0, v1, v182 op_sel_hi:[0,0,0]
	v_mfma_scale_f32_16x16x128_f8f6f4 v[78:81], v[18:25], v[202:209], 0, v1, v182 op_sel_hi:[0,0,0]
	v_mfma_scale_f32_16x16x128_f8f6f4 v[74:77], v[26:33], v[202:209], 0, v1, v182 op_sel_hi:[0,0,0]
	v_mfma_scale_f32_16x16x128_f8f6f4 v[62:65], v[18:25], v[210:217], 0, v1, v182 op_sel_hi:[0,0,0]
	v_mfma_scale_f32_16x16x128_f8f6f4 v[58:61], v[26:33], v[210:217], 0, v1, v182 op_sel_hi:[0,0,0]
	v_mfma_scale_f32_16x16x128_f8f6f4 v[46:49], v[18:25], v[218:225], 0, v1, v182 op_sel_hi:[0,0,0]
	v_mfma_scale_f32_16x16x128_f8f6f4 v[42:45], v[26:33], v[218:225], 0, v1, v182 op_sel_hi:[0,0,0]
	s_setprio 0
	s_setprio 1
	v_mfma_scale_f32_16x16x128_f8f6f4 v[86:89], v[2:9], v[194:201], 0, v1, v182 op_sel_hi:[0,0,0]
	v_mfma_scale_f32_16x16x128_f8f6f4 v[82:85], v[10:17], v[194:201], 0, v1, v182 op_sel_hi:[0,0,0]
	v_mfma_scale_f32_16x16x128_f8f6f4 v[70:73], v[2:9], v[202:209], 0, v1, v182 op_sel_hi:[0,0,0]
	v_mfma_scale_f32_16x16x128_f8f6f4 v[66:69], v[10:17], v[202:209], 0, v1, v182 op_sel_hi:[0,0,0]
	v_mfma_scale_f32_16x16x128_f8f6f4 v[54:57], v[2:9], v[210:217], 0, v1, v182 op_sel_hi:[0,0,0]
	v_mfma_scale_f32_16x16x128_f8f6f4 v[50:53], v[10:17], v[210:217], 0, v1, v182 op_sel_hi:[0,0,0]
	v_mfma_scale_f32_16x16x128_f8f6f4 v[38:41], v[2:9], v[218:225], 0, v1, v182 op_sel_hi:[0,0,0]
	v_mfma_scale_f32_16x16x128_f8f6f4 v[34:37], v[10:17], v[218:225], 0, v1, v182 op_sel_hi:[0,0,0]
	s_setprio 0
	s_barrier
; #define PG8_STAGE(bufoff, gbase, voff) do { _Pragma("unroll") for (int _i = 0; _i < 2; ++_i) \
;         __builtin_amdgcn_global_load_lds((const unsigned*)((const char*)(gbase) + (voff)[_i]), (PG8_LAS unsigned*)(lds + (bufoff) + ldsw + _i * 8192), 16, 0, 0); } while (0)
; #define PG8_LDA(dst, b, h) do { _Pragma("unroll") for (int m = 0; m < 4; ++m) _Pragma("unroll") for (int k = 0; k < 2; ++k) dst[m][k] = *(const PG8_LAS bf16x8*)(lds + PG8_SA(b, h) + aoff + m * 2048 + k * 1024); } while (0)
; #define PG8_LDB(dst, b, h) do { _Pragma("unroll") for (int n = 0; n < 2; ++n) _Pragma("unroll") for (int k = 0; k < 2; ++k) dst[n][k] = *(const PG8_LAS bf16x8*)(lds + PG8_SB(b, h) + boff + n * 2048 + k * 1024); } while (0)
; #define PG8_BAR __builtin_amdgcn_s_barrier()
; template <class Epi, class Sched, bool ALIGN_EPI = false>
; __device__ __forceinline__ void gemm_phase8(PG8_LAS unsigned char* lds, const Gemm g, const Sched& S, const Epi& E) {
;     ...
;         for (int t = 0; t < nt; t += 2) {
;             const bool last = (t == nt - 2);
;             const char* a1 = cA + (size_t)(t + 1) * kstep;
;             const char* a2 = last ? nA : cA + (size_t)(t + 2) * kstep; const char* b2 = last ? nB : cB + (size_t)(t + 2) * kstep;
;             const char* a3 = a2 + kstep; const char* b3 = b2 + kstep;
;             if (last && has_next) S.a_ready(nxt);
;             PG8_LDB(B0, 0, 0); PG8_LDB(B1, 0, 1); PG8_SCHED; PG8_LDA(At, 0, 0); PG8_STAGE(PG8_SA(1, 1), a1 + hstepA, voffA);
;             PG8_WAIT_V(8); PG8_WAIT_L(0); PG8_BAR; PG8_MMA(0, 0, At, B0); PG8_MMA(0, 1, At, B1); PG8_BAR; PG8_SCHED;
;             PG8_LDA(At, 0, 1); PG8_STAGE(PG8_SB(0, 0), b2, voffB); PG8_STAGE(PG8_SB(0, 1), b2 + hstepB, voffB); PG8_STAGE(PG8_SA(0, 0), a2, voffA);
;             PG8_WAIT_V(8); PG8_WAIT_L(0); PG8_BAR; PG8_MMA(1, 0, At, B0); PG8_MMA(1, 1, At, B1); PG8_BAR; PG8_SCHED;
;             PG8_LDB(B0, 1, 0); PG8_LDB(B1, 1, 1); PG8_SCHED; PG8_LDA(At, 1, 0); PG8_STAGE(PG8_SA(0, 1), a2 + hstepA, voffA);
;             PG8_WAIT_V(8); PG8_WAIT_L(0); PG8_BAR; PG8_MMA(0, 0, At, B0); PG8_MMA(0, 1, At, B1); PG8_BAR; PG8_SCHED;
;             PG8_LDA(At, 1, 1); PG8_STAGE(PG8_SB(1, 0), b3, voffB); PG8_STAGE(PG8_SB(1, 1), b3 + hstepB, voffB); PG8_STAGE(PG8_SA(1, 0), a3, voffA);
;             PG8_WAIT_V(8); PG8_WAIT_L(0); PG8_BAR; PG8_MMA(1, 0, At, B0); PG8_MMA(1, 1, At, B1); PG8_BAR; PG8_SCHED;
	s_add_i32 s85, 0, 0x18000
	s_add_i32 s88, 0, 0x1c000
	v_add_u32_e32 v6, s85, v184
	v_add_u32_e32 v14, s85, v185
	v_add_u32_e32 v22, s88, v184
	v_add_u32_e32 v30, s88, v185
	ds_read_b128 v[2:5], v6
	ds_read_b128 v[10:13], v6 offset:2048
	ds_read_b128 v[6:9], v14
	ds_read_b128 v[14:17], v14 offset:2048
	ds_read_b128 v[18:21], v22
	ds_read_b128 v[26:29], v22 offset:2048
	ds_read_b128 v[22:25], v30
	ds_read_b128 v[30:33], v30 offset:2048
	s_add_u32 s34, s34, 0xb0000
	s_addc_u32 s35, s35, 0
	s_mov_b32 m0, s56
	ds_read_b128 v[194:197], v191 offset:32768
	ds_read_b128 v[202:205], v191 offset:34816
	ds_read_b128 v[198:201], v192 offset:32768
	ds_read_b128 v[206:209], v192 offset:34816
	ds_read_b128 v[210:213], v191 offset:36864
	ds_read_b128 v[218:221], v191 offset:38912
	ds_read_b128 v[214:217], v192 offset:36864
	ds_read_b128 v[222:225], v192 offset:38912
	global_load_lds_dwordx4 v162, s[34:35]
	s_mov_b32 m0, s57
	s_nop 0
	global_load_lds_dwordx4 v166, s[34:35]
	s_waitcnt vmcnt(8)
	s_waitcnt lgkmcnt(0)
	s_barrier
	s_setprio 1
	s_waitcnt lgkmcnt(0)
	v_mfma_scale_f32_16x16x128_f8f6f4 v[158:161], v[2:9], v[194:201], v[158:161], v1, v182 op_sel_hi:[0,0,0]
	v_mfma_scale_f32_16x16x128_f8f6f4 v[154:157], v[10:17], v[194:201], v[154:157], v1, v182 op_sel_hi:[0,0,0]
	v_mfma_scale_f32_16x16x128_f8f6f4 v[142:145], v[2:9], v[202:209], v[142:145], v1, v182 op_sel_hi:[0,0,0]
	v_mfma_scale_f32_16x16x128_f8f6f4 v[138:141], v[10:17], v[202:209], v[138:141], v1, v182 op_sel_hi:[0,0,0]
	v_mfma_scale_f32_16x16x128_f8f6f4 v[126:129], v[2:9], v[210:217], v[126:129], v1, v182 op_sel_hi:[0,0,0]
	v_mfma_scale_f32_16x16x128_f8f6f4 v[122:125], v[10:17], v[210:217], v[122:125], v1, v182 op_sel_hi:[0,0,0]
	v_mfma_scale_f32_16x16x128_f8f6f4 v[110:113], v[2:9], v[218:225], v[110:113], v1, v182 op_sel_hi:[0,0,0]
	v_mfma_scale_f32_16x16x128_f8f6f4 v[106:109], v[10:17], v[218:225], v[106:109], v1, v182 op_sel_hi:[0,0,0]
	s_setprio 0
	s_setprio 1
	v_mfma_scale_f32_16x16x128_f8f6f4 v[150:153], v[18:25], v[194:201], v[150:153], v1, v182 op_sel_hi:[0,0,0]
	v_mfma_scale_f32_16x16x128_f8f6f4 v[146:149], v[26:33], v[194:201], v[146:149], v1, v182 op_sel_hi:[0,0,0]
	v_mfma_scale_f32_16x16x128_f8f6f4 v[134:137], v[18:25], v[202:209], v[134:137], v1, v182 op_sel_hi:[0,0,0]
	v_mfma_scale_f32_16x16x128_f8f6f4 v[130:133], v[26:33], v[202:209], v[130:133], v1, v182 op_sel_hi:[0,0,0]
	v_mfma_scale_f32_16x16x128_f8f6f4 v[118:121], v[18:25], v[210:217], v[118:121], v1, v182 op_sel_hi:[0,0,0]
	v_mfma_scale_f32_16x16x128_f8f6f4 v[114:117], v[26:33], v[210:217], v[114:117], v1, v182 op_sel_hi:[0,0,0]
	v_mfma_scale_f32_16x16x128_f8f6f4 v[102:105], v[18:25], v[218:225], v[102:105], v1, v182 op_sel_hi:[0,0,0]
	v_mfma_scale_f32_16x16x128_f8f6f4 v[98:101], v[26:33], v[218:225], v[98:101], v1, v182 op_sel_hi:[0,0,0]
	s_setprio 0
	s_barrier
	s_add_i32 s101, s85, s53
	s_add_u32 s98, s30, s12
	s_addc_u32 s99, s31, s13
	s_mov_b32 m0, s101
	ds_read_b128 v[194:197], v191 offset:49152
	ds_read_b128 v[202:205], v191 offset:51200
	ds_read_b128 v[198:201], v192 offset:49152
	ds_read_b128 v[206:209], v192 offset:51200
	ds_read_b128 v[210:213], v191 offset:53248
	ds_read_b128 v[218:221], v191 offset:55296
	ds_read_b128 v[214:217], v192 offset:53248
	ds_read_b128 v[222:225], v192 offset:55296
	global_load_lds_dwordx4 v164, s[98:99]
	s_add_i32 m0, s101, 0x2000
	s_add_u32 s30, s30, 0xb0080
	s_addc_u32 s31, s31, 0
	s_add_i32 s101, s88, s53
	global_load_lds_dwordx4 v168, s[98:99]
	s_add_u32 s98, s34, s12
	s_addc_u32 s99, s35, s13
	s_sub_u32 s98, s98, 0xb0000
	s_subb_u32 s99, s99, 0
	s_mov_b32 m0, s101
	s_nop 0
	global_load_lds_dwordx4 v164, s[30:31]
	s_add_i32 m0, s101, 0x2000
	s_nop 0
	global_load_lds_dwordx4 v168, s[30:31]
	s_mov_b32 m0, s63
	s_nop 0
	global_load_lds_dwordx4 v162, s[98:99]
	s_mov_b32 m0, s64
	s_nop 0
	global_load_lds_dwordx4 v166, s[98:99]
	s_waitcnt vmcnt(8)
	s_waitcnt lgkmcnt(0)
	s_barrier
	s_setprio 1
	s_waitcnt lgkmcnt(0)
	v_mfma_scale_f32_16x16x128_f8f6f4 v[94:97], v[2:9], v[194:201], v[94:97], v1, v182 op_sel_hi:[0,0,0]
	v_mfma_scale_f32_16x16x128_f8f6f4 v[90:93], v[10:17], v[194:201], v[90:93], v1, v182 op_sel_hi:[0,0,0]
	v_mfma_scale_f32_16x16x128_f8f6f4 v[78:81], v[2:9], v[202:209], v[78:81], v1, v182 op_sel_hi:[0,0,0]
	v_mfma_scale_f32_16x16x128_f8f6f4 v[74:77], v[10:17], v[202:209], v[74:77], v1, v182 op_sel_hi:[0,0,0]
	v_mfma_scale_f32_16x16x128_f8f6f4 v[62:65], v[2:9], v[210:217], v[62:65], v1, v182 op_sel_hi:[0,0,0]
	v_mfma_scale_f32_16x16x128_f8f6f4 v[58:61], v[10:17], v[210:217], v[58:61], v1, v182 op_sel_hi:[0,0,0]
	v_mfma_scale_f32_16x16x128_f8f6f4 v[46:49], v[2:9], v[218:225], v[46:49], v1, v182 op_sel_hi:[0,0,0]
	v_mfma_scale_f32_16x16x128_f8f6f4 v[42:45], v[10:17], v[218:225], v[42:45], v1, v182 op_sel_hi:[0,0,0]
	s_setprio 0
	s_setprio 1
	v_mfma_scale_f32_16x16x128_f8f6f4 v[86:89], v[18:25], v[194:201], v[86:89], v1, v182 op_sel_hi:[0,0,0]
	v_mfma_scale_f32_16x16x128_f8f6f4 v[82:85], v[26:33], v[194:201], v[82:85], v1, v182 op_sel_hi:[0,0,0]
	v_mfma_scale_f32_16x16x128_f8f6f4 v[70:73], v[18:25], v[202:209], v[70:73], v1, v182 op_sel_hi:[0,0,0]
	v_mfma_scale_f32_16x16x128_f8f6f4 v[66:69], v[26:33], v[202:209], v[66:69], v1, v182 op_sel_hi:[0,0,0]
	v_mfma_scale_f32_16x16x128_f8f6f4 v[54:57], v[18:25], v[210:217], v[54:57], v1, v182 op_sel_hi:[0,0,0]
	v_mfma_scale_f32_16x16x128_f8f6f4 v[50:53], v[26:33], v[210:217], v[50:53], v1, v182 op_sel_hi:[0,0,0]
	v_mfma_scale_f32_16x16x128_f8f6f4 v[38:41], v[18:25], v[218:225], v[38:41], v1, v182 op_sel_hi:[0,0,0]
	v_mfma_scale_f32_16x16x128_f8f6f4 v[34:37], v[26:33], v[218:225], v[34:37], v1, v182 op_sel_hi:[0,0,0]
	s_setprio 0
	s_barrier
	s_add_u32 s28, s28, 0x100
	s_addc_u32 s29, s29, 0
	s_add_u32 s82, s82, 0x100
	s_addc_u32 s83, s83, 0
	s_cmp_ge_u32 s84, s25
	s_mov_b32 s34, s84
	.p2align	6

; #define PG8_STAGE(bufoff, gbase, voff) do { _Pragma("unroll") for (int _i = 0; _i < 2; ++_i) \
;         __builtin_amdgcn_global_load_lds((const unsigned*)((const char*)(gbase) + (voff)[_i]), (PG8_LAS unsigned*)(lds + (bufoff) + ldsw + _i * 8192), 16, 0, 0); } while (0)
; #define PG8_LDA(dst, b, h) do { _Pragma("unroll") for (int m = 0; m < 4; ++m) _Pragma("unroll") for (int k = 0; k < 2; ++k) dst[m][k] = *(const PG8_LAS bf16x8*)(lds + PG8_SA(b, h) + aoff + m * 2048 + k * 1024); } while (0)
; #define PG8_LDB(dst, b, h) do { _Pragma("unroll") for (int n = 0; n < 2; ++n) _Pragma("unroll") for (int k = 0; k < 2; ++k) dst[n][k] = *(const PG8_LAS bf16x8*)(lds + PG8_SB(b, h) + boff + n * 2048 + k * 1024); } while (0)
; #define PG8_WAIT_V(n) asm volatile("s_waitcnt vmcnt(" #n ")" ::: "memory")
; #define PG8_WAIT_L(n) asm volatile("s_waitcnt lgkmcnt(" #n ")" ::: "memory")
; template <class Epi, class Sched, bool ALIGN_EPI = false>
; __device__ __forceinline__ void gemm_phase(PG8_LAS unsigned char* lds, const Gemm g, const Sched& S, const Epi& E) {
;     ...
;         const bool has_next = S.next(ui + 1, nxt);
;         const size_t nko = (has_next && nxt.kp > 0) ? (size_t)nxt.kp * g.kpiece * 2 : 0;
;         const char* nA = has_next ? (const char*)g.A + (size_t)nxt.pm * tstepA + (size_t)nxt.pn * astep + nko : cA; const char* nB = has_next ? (const char*)g.Bt + (size_t)nxt.pn * tstepB + nko : cB;
;         const int nt = (cur.kp < 0 ? g.K : g.kpiece) / BK;
;         for (int t = 0; t < nt; t += 2) {
;             const bool last = (t == nt - 2);
;             const char* a1 = cA + (size_t)(t + 1) * kstep;
;             const char* a2 = last ? nA : cA + (size_t)(t + 2) * kstep; const char* b2 = last ? nB : cB + (size_t)(t + 2) * kstep;
;             const char* a3 = a2 + kstep; const char* b3 = b2 + kstep;
;             if (last && has_next) S.a_ready(nxt);
;             PG8_LDB(B0, 0, 0); PG8_LDB(B1, 0, 1); PG8_SCHED; PG8_LDA(At, 0, 0); PG8_STAGE(PG8_SA(1, 1), a1 + hstepA, voffA);
;             PG8_WAIT_V(8); PG8_WAIT_L(0); PG8_BAR; PG8_MMA(0, 0, At, B0); PG8_MMA(0, 1, At, B1); PG8_BAR; PG8_SCHED;
;             PG8_LDA(At, 0, 1); PG8_STAGE(PG8_SB(0, 0), b2, voffB); PG8_STAGE(PG8_SB(0, 1), b2 + hstepB, voffB); PG8_STAGE(PG8_SA(0, 0), a2, voffA);
;             PG8_WAIT_V(8); PG8_WAIT_L(0); PG8_BAR; PG8_MMA(1, 0, At, B0); PG8_MMA(1, 1, At, B1); PG8_BAR; PG8_SCHED;
.LBB0_733:
	s_ashr_i32 s27, s26, 31
	s_lshl_b64 s[28:29], s[26:27], 20
	s_add_u32 s28, s56, s28
	s_addc_u32 s29, s57, s29
	s_and_b64 s[30:31], s[2:3], exec
	s_cselect_b32 s13, s29, s53
	s_cselect_b32 s27, s28, s52
	s_ashr_i32 s25, s24, 31
	s_lshl_b64 s[30:31], s[24:25], 20
	s_add_u32 s30, s4, s30
	s_addc_u32 s31, s5, s31
	s_and_b64 s[54:55], s[2:3], exec
	s_cselect_b32 s25, s31, s35
	s_cselect_b32 s82, s30, s34
	s_add_u32 s52, s52, 0x80080
	s_addc_u32 s53, s53, 0
	s_add_u32 s83, s34, 0x100
	s_addc_u32 s84, s35, 0
	s_mov_b32 s85, -2
	ds_read_b128 v[130:133], v165
	ds_read_b128 v[134:137], v165 offset:1024
	ds_read_b128 v[158:161], v165 offset:2048
	ds_read_b128 v[170:173], v165 offset:3072
	ds_read_b128 v[174:177], v166
	ds_read_b128 v[178:181], v166 offset:1024
	ds_read_b128 v[182:185], v166 offset:2048
	ds_read_b128 v[186:189], v166 offset:3072
	s_add_u32 s34, s52, 0xfff80080
	s_addc_u32 s35, s53, -1
	s_cmp_eq_u32 s85, 28
	s_cselect_b32 s55, s13, s35
	s_cselect_b32 s54, s27, s34
	s_cselect_b32 s35, s25, s84
	s_cselect_b32 s34, s82, s83
	s_add_i32 m0, s61, 0xc000
	ds_read_b128 v[190:193], v167
	ds_read_b128 v[194:197], v167 offset:1024
	ds_read_b128 v[198:201], v167 offset:2048
	ds_read_b128 v[202:205], v167 offset:3072
	ds_read_b128 v[206:209], v167 offset:4096
	ds_read_b128 v[210:213], v167 offset:5120
	ds_read_b128 v[214:217], v167 offset:6144
	ds_read_b128 v[218:221], v167 offset:7168
	global_load_lds_dwordx4 v150, s[52:53]
	s_add_i32 m0, s61, 0xe000
	s_nop 0
	global_load_lds_dwordx4 v152, s[52:53]
	s_waitcnt vmcnt(8)
	s_waitcnt lgkmcnt(0)
	s_barrier
	s_waitcnt lgkmcnt(0)
	v_mfma_f32_16x16x32_bf16 v[126:129], v[130:133], v[190:193], 0
	v_mfma_f32_16x16x32_bf16 v[122:125], v[158:161], v[190:193], 0
	v_mfma_f32_16x16x32_bf16 v[114:117], v[130:133], v[198:201], 0
	v_mfma_f32_16x16x32_bf16 v[106:109], v[158:161], v[198:201], 0
	v_mfma_f32_16x16x32_bf16 v[98:101], v[130:133], v[206:209], 0
	v_mfma_f32_16x16x32_bf16 v[90:93], v[158:161], v[206:209], 0
	v_mfma_f32_16x16x32_bf16 v[82:85], v[130:133], v[214:217], 0
	v_mfma_f32_16x16x32_bf16 v[74:77], v[158:161], v[214:217], 0
	v_mfma_f32_16x16x32_bf16 v[126:129], v[134:137], v[194:197], v[126:129]
	v_mfma_f32_16x16x32_bf16 v[122:125], v[170:173], v[194:197], v[122:125]
	v_mfma_f32_16x16x32_bf16 v[114:117], v[134:137], v[202:205], v[114:117]
	v_mfma_f32_16x16x32_bf16 v[106:109], v[170:173], v[202:205], v[106:109]
	v_mfma_f32_16x16x32_bf16 v[98:101], v[134:137], v[210:213], v[98:101]
	v_mfma_f32_16x16x32_bf16 v[90:93], v[170:173], v[210:213], v[90:93]
	v_mfma_f32_16x16x32_bf16 v[82:85], v[134:137], v[218:221], v[82:85]
	v_mfma_f32_16x16x32_bf16 v[74:77], v[170:173], v[218:221], v[74:77]
	v_mfma_f32_16x16x32_bf16 v[118:121], v[174:177], v[190:193], 0
	v_mfma_f32_16x16x32_bf16 v[110:113], v[182:185], v[190:193], 0
	v_mfma_f32_16x16x32_bf16 v[102:105], v[174:177], v[198:201], 0
	v_mfma_f32_16x16x32_bf16 v[94:97], v[182:185], v[198:201], 0
	v_mfma_f32_16x16x32_bf16 v[86:89], v[174:177], v[206:209], 0
	v_mfma_f32_16x16x32_bf16 v[78:81], v[182:185], v[206:209], 0
	v_mfma_f32_16x16x32_bf16 v[70:73], v[174:177], v[214:217], 0
	v_mfma_f32_16x16x32_bf16 v[66:69], v[182:185], v[214:217], 0
	v_mfma_f32_16x16x32_bf16 v[118:121], v[178:181], v[194:197], v[118:121]
	v_mfma_f32_16x16x32_bf16 v[110:113], v[186:189], v[194:197], v[110:113]
	v_mfma_f32_16x16x32_bf16 v[102:105], v[178:181], v[202:205], v[102:105]
	v_mfma_f32_16x16x32_bf16 v[94:97], v[186:189], v[202:205], v[94:97]
	v_mfma_f32_16x16x32_bf16 v[86:89], v[178:181], v[210:213], v[86:89]
	v_mfma_f32_16x16x32_bf16 v[78:81], v[186:189], v[210:213], v[78:81]
	v_mfma_f32_16x16x32_bf16 v[70:73], v[178:181], v[218:221], v[70:73]
	v_mfma_f32_16x16x32_bf16 v[66:69], v[186:189], v[218:221], v[66:69]
	s_barrier
	s_add_i32 s88, s72, s58
	s_mov_b32 m0, s88
	ds_read_b128 v[190:193], v167 offset:16384
	ds_read_b128 v[194:197], v167 offset:17408
	ds_read_b128 v[198:201], v167 offset:18432
	ds_read_b128 v[202:205], v167 offset:19456
	ds_read_b128 v[206:209], v167 offset:20480
	ds_read_b128 v[210:213], v167 offset:21504
	ds_read_b128 v[214:217], v167 offset:22528
	ds_read_b128 v[218:221], v167 offset:23552
	global_load_lds_dwordx4 v140, s[34:35]
	s_add_i32 m0, s88, 0x2000
	s_add_u32 s88, s34, 0x80000
	s_addc_u32 s89, s35, 0
	s_add_i32 s90, s73, s58
	global_load_lds_dwordx4 v144, s[34:35]
	s_mov_b32 m0, s90
	s_nop 0
	global_load_lds_dwordx4 v140, s[88:89]
	s_add_i32 m0, s90, 0x2000
	s_nop 0
	global_load_lds_dwordx4 v144, s[88:89]
	s_mov_b32 m0, s61
	s_nop 0
	global_load_lds_dwordx4 v138, s[54:55]
	s_mov_b32 m0, s62
	s_nop 0
	global_load_lds_dwordx4 v142, s[54:55]
	s_waitcnt vmcnt(8)
	s_waitcnt lgkmcnt(0)
	s_barrier
; #define PG8_STAGE(bufoff, gbase, voff) do { _Pragma("unroll") for (int _i = 0; _i < 2; ++_i) \
;         __builtin_amdgcn_global_load_lds((const unsigned*)((const char*)(gbase) + (voff)[_i]), (PG8_LAS unsigned*)(lds + (bufoff) + ldsw + _i * 8192), 16, 0, 0); } while (0)
; #define PG8_LDA(dst, b, h) do { _Pragma("unroll") for (int m = 0; m < 4; ++m) _Pragma("unroll") for (int k = 0; k < 2; ++k) dst[m][k] = *(const PG8_LAS bf16x8*)(lds + PG8_SA(b, h) + aoff + m * 2048 + k * 1024); } while (0)
; #define PG8_LDB(dst, b, h) do { _Pragma("unroll") for (int n = 0; n < 2; ++n) _Pragma("unroll") for (int k = 0; k < 2; ++k) dst[n][k] = *(const PG8_LAS bf16x8*)(lds + PG8_SB(b, h) + boff + n * 2048 + k * 1024); } while (0)
; #define PG8_MMA(ai, bj, At, Bt) do { __builtin_amdgcn_s_setprio(1); _Pragma("unroll") for (int m = 0; m < 4; ++m) _Pragma("unroll") for (int n = 0; n < 2; ++n) _Pragma("unroll") for (int k = 0; k < 2; ++k) \
;         acc[ai][bj][m][n] = __builtin_amdgcn_mfma_f32_16x16x32_bf16(Bt[n][k], At[m][k], acc[ai][bj][m][n], 0, 0, 0); __builtin_amdgcn_s_setprio(0); } while (0)
; #define PG8_WAIT_V(n) asm volatile("s_waitcnt vmcnt(" #n ")" ::: "memory")
; #define PG8_WAIT_L(n) asm volatile("s_waitcnt lgkmcnt(" #n ")" ::: "memory")
; #define PG8_BAR __builtin_amdgcn_s_barrier()
; #define PG8_SCHED __builtin_amdgcn_sched_barrier(0)
; #define PG8_STAGE(bufoff, gbase, voff) do { _Pragma("unroll") for (int _i = 0; _i < 2; ++_i) \
;         __builtin_amdgcn_global_load_lds((const unsigned*)((const char*)(gbase) + (voff)[_i]), (PG8_LAS unsigned*)(lds + (bufoff) + ldsw + _i * 8192), 16, 0, 0); } while (0)
; #define PG8_WAIT_V(n) asm volatile("s_waitcnt vmcnt(" #n ")" ::: "memory")
; template <class Epi, class Sched, bool ALIGN_EPI = false>
; __device__ __forceinline__ void gemm_phase(PG8_LAS unsigned char* lds, const Gemm g, const Sched& S, const Epi& E) {
;     ...
;             PG8_WAIT_V(8); PG8_WAIT_L(0); PG8_BAR; PG8_MMA(1, 0, At, B0); PG8_MMA(1, 1, At, B1); PG8_BAR; PG8_SCHED;
;             PG8_LDB(B0, 1, 0); PG8_LDB(B1, 1, 1); PG8_SCHED; PG8_LDA(At, 1, 0); PG8_STAGE(PG8_SA(0, 1), a2 + hstepA, voffA);
;             PG8_WAIT_V(8); PG8_WAIT_L(0); PG8_BAR; PG8_MMA(0, 0, At, B0); PG8_MMA(0, 1, At, B1); PG8_BAR; PG8_SCHED;
;             PG8_LDA(At, 1, 1); PG8_STAGE(PG8_SB(1, 0), b3, voffB); PG8_STAGE(PG8_SB(1, 1), b3 + hstepB, voffB); PG8_STAGE(PG8_SA(1, 0), a3, voffA);
	s_waitcnt lgkmcnt(0)
	v_mfma_f32_16x16x32_bf16 v[62:65], v[130:133], v[190:193], 0
	v_mfma_f32_16x16x32_bf16 v[58:61], v[158:161], v[190:193], 0
	v_mfma_f32_16x16x32_bf16 v[54:57], v[130:133], v[198:201], 0
	v_mfma_f32_16x16x32_bf16 v[46:49], v[158:161], v[198:201], 0
	v_mfma_f32_16x16x32_bf16 v[38:41], v[130:133], v[206:209], 0
	v_mfma_f32_16x16x32_bf16 v[30:33], v[158:161], v[206:209], 0
	v_mfma_f32_16x16x32_bf16 v[22:25], v[130:133], v[214:217], 0
	v_mfma_f32_16x16x32_bf16 v[14:17], v[158:161], v[214:217], 0
	v_mfma_f32_16x16x32_bf16 v[62:65], v[134:137], v[194:197], v[62:65]
	v_mfma_f32_16x16x32_bf16 v[58:61], v[170:173], v[194:197], v[58:61]
	v_mfma_f32_16x16x32_bf16 v[54:57], v[134:137], v[202:205], v[54:57]
	v_mfma_f32_16x16x32_bf16 v[46:49], v[170:173], v[202:205], v[46:49]
	v_mfma_f32_16x16x32_bf16 v[38:41], v[134:137], v[210:213], v[38:41]
	v_mfma_f32_16x16x32_bf16 v[30:33], v[170:173], v[210:213], v[30:33]
	v_mfma_f32_16x16x32_bf16 v[22:25], v[134:137], v[218:221], v[22:25]
	v_mfma_f32_16x16x32_bf16 v[14:17], v[170:173], v[218:221], v[14:17]
	v_mfma_f32_16x16x32_bf16 v[50:53], v[174:177], v[190:193], 0
	v_mfma_f32_16x16x32_bf16 v[42:45], v[182:185], v[190:193], 0
	v_mfma_f32_16x16x32_bf16 v[34:37], v[174:177], v[198:201], 0
	v_mfma_f32_16x16x32_bf16 v[26:29], v[182:185], v[198:201], 0
	v_mfma_f32_16x16x32_bf16 v[18:21], v[174:177], v[206:209], 0
	v_mfma_f32_16x16x32_bf16 v[10:13], v[182:185], v[206:209], 0
	v_mfma_f32_16x16x32_bf16 v[6:9], v[174:177], v[214:217], 0
	v_mfma_f32_16x16x32_bf16 v[2:5], v[182:185], v[214:217], 0
	v_mfma_f32_16x16x32_bf16 v[50:53], v[178:181], v[194:197], v[50:53]
	v_mfma_f32_16x16x32_bf16 v[42:45], v[186:189], v[194:197], v[42:45]
	v_mfma_f32_16x16x32_bf16 v[34:37], v[178:181], v[202:205], v[34:37]
	v_mfma_f32_16x16x32_bf16 v[26:29], v[186:189], v[202:205], v[26:29]
	v_mfma_f32_16x16x32_bf16 v[18:21], v[178:181], v[210:213], v[18:21]
	v_mfma_f32_16x16x32_bf16 v[10:13], v[186:189], v[210:213], v[10:13]
	v_mfma_f32_16x16x32_bf16 v[6:9], v[178:181], v[218:221], v[6:9]
	v_mfma_f32_16x16x32_bf16 v[2:5], v[186:189], v[218:221], v[2:5]
	s_barrier
	s_add_i32 s88, 0, 0x18000
	v_add_u32_e32 v146, s88, v164
	s_add_i32 s89, 0, 0x1c000
	ds_read_b128 v[130:133], v146
	ds_read_b128 v[134:137], v146 offset:1024
	ds_read_b128 v[158:161], v146 offset:2048
	ds_read_b128 v[170:173], v146 offset:3072
	v_add_u32_e32 v146, s89, v164
	ds_read_b128 v[174:177], v146
	ds_read_b128 v[178:181], v146 offset:1024
	ds_read_b128 v[182:185], v146 offset:2048
	ds_read_b128 v[186:189], v146 offset:3072
	s_add_u32 s54, s54, 0x80000
	s_addc_u32 s55, s55, 0
	s_mov_b32 m0, s63
	ds_read_b128 v[190:193], v167 offset:32768
	ds_read_b128 v[194:197], v167 offset:33792
	ds_read_b128 v[198:201], v167 offset:34816
	ds_read_b128 v[202:205], v167 offset:35840
	ds_read_b128 v[206:209], v167 offset:36864
	ds_read_b128 v[210:213], v167 offset:37888
	ds_read_b128 v[214:217], v167 offset:38912
	ds_read_b128 v[218:221], v167 offset:39936
	global_load_lds_dwordx4 v138, s[54:55]
	s_mov_b32 m0, s64
	s_nop 0
	global_load_lds_dwordx4 v142, s[54:55]
	s_waitcnt vmcnt(8)
	s_waitcnt lgkmcnt(0)
	s_barrier
	s_waitcnt lgkmcnt(0)
	v_mfma_f32_16x16x32_bf16 v[126:129], v[130:133], v[190:193], v[126:129]
	v_mfma_f32_16x16x32_bf16 v[122:125], v[158:161], v[190:193], v[122:125]
	v_mfma_f32_16x16x32_bf16 v[114:117], v[130:133], v[198:201], v[114:117]
	v_mfma_f32_16x16x32_bf16 v[106:109], v[158:161], v[198:201], v[106:109]
	v_mfma_f32_16x16x32_bf16 v[98:101], v[130:133], v[206:209], v[98:101]
	v_mfma_f32_16x16x32_bf16 v[90:93], v[158:161], v[206:209], v[90:93]
	v_mfma_f32_16x16x32_bf16 v[82:85], v[130:133], v[214:217], v[82:85]
	v_mfma_f32_16x16x32_bf16 v[74:77], v[158:161], v[214:217], v[74:77]
	v_mfma_f32_16x16x32_bf16 v[126:129], v[134:137], v[194:197], v[126:129]
	v_mfma_f32_16x16x32_bf16 v[122:125], v[170:173], v[194:197], v[122:125]
	v_mfma_f32_16x16x32_bf16 v[114:117], v[134:137], v[202:205], v[114:117]
	v_mfma_f32_16x16x32_bf16 v[106:109], v[170:173], v[202:205], v[106:109]
	v_mfma_f32_16x16x32_bf16 v[98:101], v[134:137], v[210:213], v[98:101]
	v_mfma_f32_16x16x32_bf16 v[90:93], v[170:173], v[210:213], v[90:93]
	v_mfma_f32_16x16x32_bf16 v[82:85], v[134:137], v[218:221], v[82:85]
	v_mfma_f32_16x16x32_bf16 v[74:77], v[170:173], v[218:221], v[74:77]
	v_mfma_f32_16x16x32_bf16 v[118:121], v[174:177], v[190:193], v[118:121]
	v_mfma_f32_16x16x32_bf16 v[110:113], v[182:185], v[190:193], v[110:113]
	v_mfma_f32_16x16x32_bf16 v[102:105], v[174:177], v[198:201], v[102:105]
	v_mfma_f32_16x16x32_bf16 v[94:97], v[182:185], v[198:201], v[94:97]
	v_mfma_f32_16x16x32_bf16 v[86:89], v[174:177], v[206:209], v[86:89]
	v_mfma_f32_16x16x32_bf16 v[78:81], v[182:185], v[206:209], v[78:81]
	v_mfma_f32_16x16x32_bf16 v[70:73], v[174:177], v[214:217], v[70:73]
	v_mfma_f32_16x16x32_bf16 v[66:69], v[182:185], v[214:217], v[66:69]
	v_mfma_f32_16x16x32_bf16 v[118:121], v[178:181], v[194:197], v[118:121]
	v_mfma_f32_16x16x32_bf16 v[110:113], v[186:189], v[194:197], v[110:113]
	v_mfma_f32_16x16x32_bf16 v[102:105], v[178:181], v[202:205], v[102:105]
	v_mfma_f32_16x16x32_bf16 v[94:97], v[186:189], v[202:205], v[94:97]
	v_mfma_f32_16x16x32_bf16 v[86:89], v[178:181], v[210:213], v[86:89]
	v_mfma_f32_16x16x32_bf16 v[78:81], v[186:189], v[210:213], v[78:81]
	v_mfma_f32_16x16x32_bf16 v[70:73], v[178:181], v[218:221], v[70:73]
	v_mfma_f32_16x16x32_bf16 v[66:69], v[186:189], v[218:221], v[66:69]
	s_barrier
; #define PG8_STAGE(bufoff, gbase, voff) do { _Pragma("unroll") for (int _i = 0; _i < 2; ++_i) \
;         __builtin_amdgcn_global_load_lds((const unsigned*)((const char*)(gbase) + (voff)[_i]), (PG8_LAS unsigned*)(lds + (bufoff) + ldsw + _i * 8192), 16, 0, 0); } while (0)
; #define PG8_LDA(dst, b, h) do { _Pragma("unroll") for (int m = 0; m < 4; ++m) _Pragma("unroll") for (int k = 0; k < 2; ++k) dst[m][k] = *(const PG8_LAS bf16x8*)(lds + PG8_SA(b, h) + aoff + m * 2048 + k * 1024); } while (0)
; #define PG8_MMA(ai, bj, At, Bt) do { __builtin_amdgcn_s_setprio(1); _Pragma("unroll") for (int m = 0; m < 4; ++m) _Pragma("unroll") for (int n = 0; n < 2; ++n) _Pragma("unroll") for (int k = 0; k < 2; ++k) \
;         acc[ai][bj][m][n] = __builtin_amdgcn_mfma_f32_16x16x32_bf16(Bt[n][k], At[m][k], acc[ai][bj][m][n], 0, 0, 0); __builtin_amdgcn_s_setprio(0); } while (0)
; #define PG8_WAIT_V(n) asm volatile("s_waitcnt vmcnt(" #n ")" ::: "memory")
; #define PG8_WAIT_L(n) asm volatile("s_waitcnt lgkmcnt(" #n ")" ::: "memory")
; #define PG8_BAR __builtin_amdgcn_s_barrier()
; #define PG8_SCHED __builtin_amdgcn_sched_barrier(0)
; #define PG8_STAGE(bufoff, gbase, voff) do { _Pragma("unroll") for (int _i = 0; _i < 2; ++_i) \
;         __builtin_amdgcn_global_load_lds((const unsigned*)((const char*)(gbase) + (voff)[_i]), (PG8_LAS unsigned*)(lds + (bufoff) + ldsw + _i * 8192), 16, 0, 0); } while (0)
; #define PG8_WAIT_V(n) asm volatile("s_waitcnt vmcnt(" #n ")" ::: "memory")
; #define PG8_WAIT_L(n) asm volatile("s_waitcnt lgkmcnt(" #n ")" ::: "memory")
; template <class Epi, class Sched, bool ALIGN_EPI = false>
; __device__ __forceinline__ void gemm_phase(PG8_LAS unsigned char* lds, const Gemm g, const Sched& S, const Epi& E) {
;     ...
;         for (int t = 0; t < nt; t += 2) {
;             const bool last = (t == nt - 2);
;             const char* a1 = cA + (size_t)(t + 1) * kstep;
;             const char* a2 = last ? nA : cA + (size_t)(t + 2) * kstep; const char* b2 = last ? nB : cB + (size_t)(t + 2) * kstep;
;             const char* a3 = a2 + kstep; const char* b3 = b2 + kstep;
;     ...
;             PG8_LDA(At, 1, 1); PG8_STAGE(PG8_SB(1, 0), b3, voffB); PG8_STAGE(PG8_SB(1, 1), b3 + hstepB, voffB); PG8_STAGE(PG8_SA(1, 0), a3, voffA);
;             PG8_WAIT_V(8); PG8_WAIT_L(0); PG8_BAR; PG8_MMA(1, 0, At, B0); PG8_MMA(1, 1, At, B1); PG8_BAR; PG8_SCHED;
	s_add_i32 s101, s88, s58
	s_add_u32 s98, s34, s10
	s_addc_u32 s99, s35, s11
	s_mov_b32 m0, s101
	ds_read_b128 v[190:193], v167 offset:49152
	ds_read_b128 v[194:197], v167 offset:50176
	ds_read_b128 v[198:201], v167 offset:51200
	ds_read_b128 v[202:205], v167 offset:52224
	ds_read_b128 v[206:209], v167 offset:53248
	ds_read_b128 v[210:213], v167 offset:54272
	ds_read_b128 v[214:217], v167 offset:55296
	ds_read_b128 v[218:221], v167 offset:56320
	global_load_lds_dwordx4 v140, s[98:99]
	s_add_i32 m0, s101, 0x2000
	s_add_u32 s34, s34, 0x80080
	s_addc_u32 s35, s35, 0
	s_add_i32 s101, s89, s58
	global_load_lds_dwordx4 v144, s[98:99]
	s_add_u32 s98, s54, s10
	s_addc_u32 s99, s55, s11
	s_sub_u32 s98, s98, 0x80000
	s_subb_u32 s99, s99, 0
	s_mov_b32 m0, s101
	s_nop 0
	global_load_lds_dwordx4 v140, s[34:35]
	s_add_i32 m0, s101, 0x2000
	s_nop 0
	global_load_lds_dwordx4 v144, s[34:35]
	s_mov_b32 m0, s70
	s_nop 0
	global_load_lds_dwordx4 v138, s[98:99]
	s_mov_b32 m0, s71
	s_nop 0
	global_load_lds_dwordx4 v142, s[98:99]
	s_waitcnt vmcnt(8)
	s_waitcnt lgkmcnt(0)
	s_barrier
	s_waitcnt lgkmcnt(0)
	v_mfma_f32_16x16x32_bf16 v[62:65], v[130:133], v[190:193], v[62:65]
	v_mfma_f32_16x16x32_bf16 v[58:61], v[158:161], v[190:193], v[58:61]
	v_mfma_f32_16x16x32_bf16 v[54:57], v[130:133], v[198:201], v[54:57]
	v_mfma_f32_16x16x32_bf16 v[46:49], v[158:161], v[198:201], v[46:49]
	v_mfma_f32_16x16x32_bf16 v[38:41], v[130:133], v[206:209], v[38:41]
	v_mfma_f32_16x16x32_bf16 v[30:33], v[158:161], v[206:209], v[30:33]
	v_mfma_f32_16x16x32_bf16 v[22:25], v[130:133], v[214:217], v[22:25]
	v_mfma_f32_16x16x32_bf16 v[14:17], v[158:161], v[214:217], v[14:17]
	v_mfma_f32_16x16x32_bf16 v[62:65], v[134:137], v[194:197], v[62:65]
	v_mfma_f32_16x16x32_bf16 v[58:61], v[170:173], v[194:197], v[58:61]
	v_mfma_f32_16x16x32_bf16 v[54:57], v[134:137], v[202:205], v[54:57]
	v_mfma_f32_16x16x32_bf16 v[46:49], v[170:173], v[202:205], v[46:49]
	v_mfma_f32_16x16x32_bf16 v[38:41], v[134:137], v[210:213], v[38:41]
	v_mfma_f32_16x16x32_bf16 v[30:33], v[170:173], v[210:213], v[30:33]
	v_mfma_f32_16x16x32_bf16 v[22:25], v[134:137], v[218:221], v[22:25]
	v_mfma_f32_16x16x32_bf16 v[14:17], v[170:173], v[218:221], v[14:17]
	v_mfma_f32_16x16x32_bf16 v[50:53], v[174:177], v[190:193], v[50:53]
	v_mfma_f32_16x16x32_bf16 v[42:45], v[182:185], v[190:193], v[42:45]
	v_mfma_f32_16x16x32_bf16 v[34:37], v[174:177], v[198:201], v[34:37]
	v_mfma_f32_16x16x32_bf16 v[26:29], v[182:185], v[198:201], v[26:29]
	v_mfma_f32_16x16x32_bf16 v[18:21], v[174:177], v[206:209], v[18:21]
	v_mfma_f32_16x16x32_bf16 v[10:13], v[182:185], v[206:209], v[10:13]
	v_mfma_f32_16x16x32_bf16 v[6:9], v[174:177], v[214:217], v[6:9]
	v_mfma_f32_16x16x32_bf16 v[2:5], v[182:185], v[214:217], v[2:5]
	v_mfma_f32_16x16x32_bf16 v[50:53], v[178:181], v[194:197], v[50:53]
	v_mfma_f32_16x16x32_bf16 v[42:45], v[186:189], v[194:197], v[42:45]
	v_mfma_f32_16x16x32_bf16 v[34:37], v[178:181], v[202:205], v[34:37]
	v_mfma_f32_16x16x32_bf16 v[26:29], v[186:189], v[202:205], v[26:29]
	v_mfma_f32_16x16x32_bf16 v[18:21], v[178:181], v[210:213], v[18:21]
	v_mfma_f32_16x16x32_bf16 v[10:13], v[186:189], v[210:213], v[10:13]
	v_mfma_f32_16x16x32_bf16 v[6:9], v[178:181], v[218:221], v[6:9]
	v_mfma_f32_16x16x32_bf16 v[2:5], v[186:189], v[218:221], v[2:5]
	s_barrier
	s_add_i32 s85, s85, 2
	s_add_u32 s52, s52, 0x100
	s_addc_u32 s53, s53, 0
	s_add_u32 s83, s83, 0x100
	s_addc_u32 s84, s84, 0
	s_cmp_gt_u32 s85, 29
	.p2align	6

; #define PG8_STAGE(bufoff, gbase, voff) do { _Pragma("unroll") for (int _i = 0; _i < 2; ++_i) \
;         __builtin_amdgcn_global_load_lds((const unsigned*)((const char*)(gbase) + (voff)[_i]), (PG8_LAS unsigned*)(lds + (bufoff) + ldsw + _i * 8192), 16, 0, 0); } while (0)
; #define PG8_LDA(dst, b, h) do { _Pragma("unroll") for (int m = 0; m < 4; ++m) _Pragma("unroll") for (int k = 0; k < 2; ++k) dst[m][k] = *(const PG8_LAS bf16x8*)(lds + PG8_SA(b, h) + aoff + m * 2048 + k * 1024); } while (0)
; #define PG8_LDB(dst, b, h) do { _Pragma("unroll") for (int n = 0; n < 2; ++n) _Pragma("unroll") for (int k = 0; k < 2; ++k) dst[n][k] = *(const PG8_LAS bf16x8*)(lds + PG8_SB(b, h) + boff + n * 2048 + k * 1024); } while (0)
; #define PG8_WAIT_V(n) asm volatile("s_waitcnt vmcnt(" #n ")" ::: "memory")
; #define PG8_WAIT_L(n) asm volatile("s_waitcnt lgkmcnt(" #n ")" ::: "memory")
; template <class Epi, class Sched, bool ALIGN_EPI = false>
; __device__ __forceinline__ void gemm_phase8(PG8_LAS unsigned char* lds, const Gemm g, const Sched& S, const Epi& E) {
;     ...
;         const bool has_next = S.next(ui + 1, nxt);
;         const size_t nko = (has_next && nxt.kp > 0) ? (size_t)nxt.kp * g.kpiece : 0;
;         const char* nA = has_next ? (const char*)g.A + (size_t)nxt.pm * tstepA + (size_t)nxt.pn * astep + nko : cA; const char* nB = has_next ? (const char*)g.Bt + (size_t)nxt.pn * tstepB + nko : cB;
;         const int nt = (cur.kp < 0 ? g.K : g.kpiece) / 128;
;         for (int t = 0; t < nt; t += 2) {
;             const bool last = (t == nt - 2);
;             const char* a1 = cA + (size_t)(t + 1) * kstep;
;             const char* a2 = last ? nA : cA + (size_t)(t + 2) * kstep; const char* b2 = last ? nB : cB + (size_t)(t + 2) * kstep;
;             const char* a3 = a2 + kstep; const char* b3 = b2 + kstep;
;             if (last && has_next) S.a_ready(nxt);
;             PG8_LDB(B0, 0, 0); PG8_LDB(B1, 0, 1); PG8_SCHED; PG8_LDA(At, 0, 0); PG8_STAGE(PG8_SA(1, 1), a1 + hstepA, voffA);
;             PG8_WAIT_V(8); PG8_WAIT_L(0); PG8_BAR; PG8_MMA(0, 0, At, B0); PG8_MMA(0, 1, At, B1); PG8_BAR; PG8_SCHED;
;             PG8_LDA(At, 0, 1); PG8_STAGE(PG8_SB(0, 0), b2, voffB); PG8_STAGE(PG8_SB(0, 1), b2 + hstepB, voffB); PG8_STAGE(PG8_SA(0, 0), a2, voffA);
;             PG8_WAIT_V(8); PG8_WAIT_L(0); PG8_BAR; PG8_MMA(1, 0, At, B0); PG8_MMA(1, 1, At, B1); PG8_BAR; PG8_SCHED;
.LBB0_1186:
	s_cmp_gt_i32 s0, 0
	s_cselect_b64 s[24:25], -1, 0
	s_and_b64 s[24:25], s[22:23], s[24:25]
	s_lshl_b64 s[26:27], s[0:1], 9
	s_and_b64 s[24:25], s[24:25], exec
	s_cselect_b32 s54, s27, 0
	s_cselect_b32 s55, s26, 0
	s_ashr_i32 s19, s18, 31
	s_lshl_b64 s[24:25], s[18:19], 19
	s_add_u32 s19, s33, s24
	s_addc_u32 s21, s60, s25
	s_add_u32 s24, s19, s55
	s_addc_u32 s25, s21, s54
	s_and_b64 s[26:27], s[22:23], exec
	s_cselect_b32 s19, s25, s57
	s_cselect_b32 s31, s24, s56
	s_ashr_i32 s21, s20, 31
	s_lshl_b64 s[26:27], s[20:21], 19
	s_add_u32 s21, s2, s26
	s_addc_u32 s27, s3, s27
	s_add_u32 s26, s21, s55
	s_addc_u32 s27, s27, s54
	s_and_b64 s[54:55], s[22:23], exec
	s_cselect_b32 s21, s27, s35
	s_cselect_b32 s75, s26, s34
	s_cmp_gt_i32 s30, -1
	s_cselect_b64 s[54:55], -1, 0
	s_cmp_lt_i32 s30, 0
	s_cselect_b32 s76, 16, 4
	s_add_i32 s77, s76, -2
	s_add_u32 s56, s56, 0x40080
	s_addc_u32 s57, s57, 0
	s_add_u32 s78, s34, 0x100
	s_mov_b32 s58, 0
	s_addc_u32 s79, s35, 0
	ds_read_b128 v[18:21], v187
	ds_read_b128 v[26:29], v187 offset:2048
	ds_read_b128 v[22:25], v188
	ds_read_b128 v[30:33], v188 offset:2048
	ds_read_b128 v[2:5], v189
	ds_read_b128 v[10:13], v189 offset:2048
	ds_read_b128 v[6:9], v190
	ds_read_b128 v[14:17], v190 offset:2048
	s_add_i32 s80, s58, 2
	s_add_u32 s34, s56, 0xfffc0080
	s_addc_u32 s35, s57, -1
	s_cmp_eq_u32 s77, s58
	s_cselect_b32 s58, s31, s34
	s_cselect_b32 s59, s19, s35
	s_cselect_b32 s35, s21, s79
	s_cselect_b32 s34, s75, s78
	s_add_i32 m0, s29, 0xc000
	ds_read_b128 v[174:177], v191
	ds_read_b128 v[194:197], v191 offset:2048
	ds_read_b128 v[178:181], v192
	ds_read_b128 v[198:201], v192 offset:2048
	ds_read_b128 v[202:205], v191 offset:4096
	ds_read_b128 v[210:213], v191 offset:6144
	ds_read_b128 v[206:209], v192 offset:4096
	ds_read_b128 v[214:217], v192 offset:6144
	global_load_lds_dwordx4 v170, s[56:57]
	s_add_i32 m0, s29, 0xe000
	s_nop 0
	global_load_lds_dwordx4 v172, s[56:57]
	s_waitcnt vmcnt(8)
	s_waitcnt lgkmcnt(0)
	s_barrier
	s_setprio 1
	s_waitcnt lgkmcnt(0)
	v_mfma_scale_f32_16x16x128_f8f6f4 v[158:161], v[18:25], v[174:181], 0, v1, v182 op_sel_hi:[0,0,0]
	v_mfma_scale_f32_16x16x128_f8f6f4 v[154:157], v[26:33], v[174:181], 0, v1, v182 op_sel_hi:[0,0,0]
	v_mfma_scale_f32_16x16x128_f8f6f4 v[150:153], v[18:25], v[194:201], 0, v1, v182 op_sel_hi:[0,0,0]
	v_mfma_scale_f32_16x16x128_f8f6f4 v[138:141], v[26:33], v[194:201], 0, v1, v182 op_sel_hi:[0,0,0]
	v_mfma_scale_f32_16x16x128_f8f6f4 v[130:133], v[18:25], v[202:209], 0, v1, v182 op_sel_hi:[0,0,0]
	v_mfma_scale_f32_16x16x128_f8f6f4 v[122:125], v[26:33], v[202:209], 0, v1, v182 op_sel_hi:[0,0,0]
	v_mfma_scale_f32_16x16x128_f8f6f4 v[118:121], v[18:25], v[210:217], 0, v1, v182 op_sel_hi:[0,0,0]
	v_mfma_scale_f32_16x16x128_f8f6f4 v[106:109], v[26:33], v[210:217], 0, v1, v182 op_sel_hi:[0,0,0]
	s_setprio 0
	s_setprio 1
	v_mfma_scale_f32_16x16x128_f8f6f4 v[146:149], v[2:9], v[174:181], 0, v1, v182 op_sel_hi:[0,0,0]
	v_mfma_scale_f32_16x16x128_f8f6f4 v[142:145], v[10:17], v[174:181], 0, v1, v182 op_sel_hi:[0,0,0]
	v_mfma_scale_f32_16x16x128_f8f6f4 v[134:137], v[2:9], v[194:201], 0, v1, v182 op_sel_hi:[0,0,0]
	v_mfma_scale_f32_16x16x128_f8f6f4 v[126:129], v[10:17], v[194:201], 0, v1, v182 op_sel_hi:[0,0,0]
	v_mfma_scale_f32_16x16x128_f8f6f4 v[114:117], v[2:9], v[202:209], 0, v1, v182 op_sel_hi:[0,0,0]
	v_mfma_scale_f32_16x16x128_f8f6f4 v[110:113], v[10:17], v[202:209], 0, v1, v182 op_sel_hi:[0,0,0]
	v_mfma_scale_f32_16x16x128_f8f6f4 v[102:105], v[2:9], v[210:217], 0, v1, v182 op_sel_hi:[0,0,0]
	v_mfma_scale_f32_16x16x128_f8f6f4 v[98:101], v[10:17], v[210:217], 0, v1, v182 op_sel_hi:[0,0,0]
	s_setprio 0
	s_barrier
	s_add_i32 s81, s71, s61
	s_mov_b32 m0, s81
	ds_read_b128 v[194:197], v191 offset:16384
	ds_read_b128 v[202:205], v191 offset:18432
	ds_read_b128 v[198:201], v192 offset:16384
	ds_read_b128 v[206:209], v192 offset:18432
	ds_read_b128 v[210:213], v191 offset:20480
	ds_read_b128 v[218:221], v191 offset:22528
	ds_read_b128 v[214:217], v192 offset:20480
	ds_read_b128 v[222:225], v192 offset:22528
	global_load_lds_dwordx4 v164, s[34:35]
	s_add_i32 m0, s81, 0x2000
	s_add_u32 s82, s34, 0x40000
	s_addc_u32 s83, s35, 0
	s_add_i32 s81, s72, s61
	global_load_lds_dwordx4 v168, s[34:35]
	s_mov_b32 m0, s81
	s_nop 0
	global_load_lds_dwordx4 v164, s[82:83]
	s_add_i32 m0, s81, 0x2000
	s_nop 0
	global_load_lds_dwordx4 v168, s[82:83]
	s_mov_b32 m0, s29
	s_nop 0
	global_load_lds_dwordx4 v162, s[58:59]
	s_mov_b32 m0, s53
	s_nop 0
	global_load_lds_dwordx4 v166, s[58:59]
	s_waitcnt vmcnt(8)
	s_waitcnt lgkmcnt(0)
	s_barrier
	s_setprio 1
	s_waitcnt lgkmcnt(0)
	v_mfma_scale_f32_16x16x128_f8f6f4 v[94:97], v[18:25], v[194:201], 0, v1, v182 op_sel_hi:[0,0,0]
	v_mfma_scale_f32_16x16x128_f8f6f4 v[90:93], v[26:33], v[194:201], 0, v1, v182 op_sel_hi:[0,0,0]
	v_mfma_scale_f32_16x16x128_f8f6f4 v[82:85], v[18:25], v[202:209], 0, v1, v182 op_sel_hi:[0,0,0]
	v_mfma_scale_f32_16x16x128_f8f6f4 v[74:77], v[26:33], v[202:209], 0, v1, v182 op_sel_hi:[0,0,0]
	v_mfma_scale_f32_16x16x128_f8f6f4 v[66:69], v[18:25], v[210:217], 0, v1, v182 op_sel_hi:[0,0,0]
	v_mfma_scale_f32_16x16x128_f8f6f4 v[58:61], v[26:33], v[210:217], 0, v1, v182 op_sel_hi:[0,0,0]
	v_mfma_scale_f32_16x16x128_f8f6f4 v[50:53], v[18:25], v[218:225], 0, v1, v182 op_sel_hi:[0,0,0]
	v_mfma_scale_f32_16x16x128_f8f6f4 v[42:45], v[26:33], v[218:225], 0, v1, v182 op_sel_hi:[0,0,0]
	s_setprio 0
	s_setprio 1
	v_mfma_scale_f32_16x16x128_f8f6f4 v[86:89], v[2:9], v[194:201], 0, v1, v182 op_sel_hi:[0,0,0]
	v_mfma_scale_f32_16x16x128_f8f6f4 v[78:81], v[10:17], v[194:201], 0, v1, v182 op_sel_hi:[0,0,0]
	v_mfma_scale_f32_16x16x128_f8f6f4 v[70:73], v[2:9], v[202:209], 0, v1, v182 op_sel_hi:[0,0,0]
	v_mfma_scale_f32_16x16x128_f8f6f4 v[62:65], v[10:17], v[202:209], 0, v1, v182 op_sel_hi:[0,0,0]
	v_mfma_scale_f32_16x16x128_f8f6f4 v[54:57], v[2:9], v[210:217], 0, v1, v182 op_sel_hi:[0,0,0]
	v_mfma_scale_f32_16x16x128_f8f6f4 v[46:49], v[10:17], v[210:217], 0, v1, v182 op_sel_hi:[0,0,0]
	v_mfma_scale_f32_16x16x128_f8f6f4 v[38:41], v[2:9], v[218:225], 0, v1, v182 op_sel_hi:[0,0,0]
	v_mfma_scale_f32_16x16x128_f8f6f4 v[34:37], v[10:17], v[218:225], 0, v1, v182 op_sel_hi:[0,0,0]
	s_setprio 0
	s_barrier
; #define PG8_STAGE(bufoff, gbase, voff) do { _Pragma("unroll") for (int _i = 0; _i < 2; ++_i) \
;         __builtin_amdgcn_global_load_lds((const unsigned*)((const char*)(gbase) + (voff)[_i]), (PG8_LAS unsigned*)(lds + (bufoff) + ldsw + _i * 8192), 16, 0, 0); } while (0)
; #define PG8_LDA(dst, b, h) do { _Pragma("unroll") for (int m = 0; m < 4; ++m) _Pragma("unroll") for (int k = 0; k < 2; ++k) dst[m][k] = *(const PG8_LAS bf16x8*)(lds + PG8_SA(b, h) + aoff + m * 2048 + k * 1024); } while (0)
; #define PG8_LDB(dst, b, h) do { _Pragma("unroll") for (int n = 0; n < 2; ++n) _Pragma("unroll") for (int k = 0; k < 2; ++k) dst[n][k] = *(const PG8_LAS bf16x8*)(lds + PG8_SB(b, h) + boff + n * 2048 + k * 1024); } while (0)
; #define PG8_BAR __builtin_amdgcn_s_barrier()
; template <class Epi, class Sched, bool ALIGN_EPI = false>
; __device__ __forceinline__ void gemm_phase8(PG8_LAS unsigned char* lds, const Gemm g, const Sched& S, const Epi& E) {
;     ...
;         for (int t = 0; t < nt; t += 2) {
;             const bool last = (t == nt - 2);
;             const char* a1 = cA + (size_t)(t + 1) * kstep;
;             const char* a2 = last ? nA : cA + (size_t)(t + 2) * kstep; const char* b2 = last ? nB : cB + (size_t)(t + 2) * kstep;
;             const char* a3 = a2 + kstep; const char* b3 = b2 + kstep;
;             if (last && has_next) S.a_ready(nxt);
;             PG8_LDB(B0, 0, 0); PG8_LDB(B1, 0, 1); PG8_SCHED; PG8_LDA(At, 0, 0); PG8_STAGE(PG8_SA(1, 1), a1 + hstepA, voffA);
;             PG8_WAIT_V(8); PG8_WAIT_L(0); PG8_BAR; PG8_MMA(0, 0, At, B0); PG8_MMA(0, 1, At, B1); PG8_BAR; PG8_SCHED;
;             PG8_LDA(At, 0, 1); PG8_STAGE(PG8_SB(0, 0), b2, voffB); PG8_STAGE(PG8_SB(0, 1), b2 + hstepB, voffB); PG8_STAGE(PG8_SA(0, 0), a2, voffA);
;             PG8_WAIT_V(8); PG8_WAIT_L(0); PG8_BAR; PG8_MMA(1, 0, At, B0); PG8_MMA(1, 1, At, B1); PG8_BAR; PG8_SCHED;
;             PG8_LDB(B0, 1, 0); PG8_LDB(B1, 1, 1); PG8_SCHED; PG8_LDA(At, 1, 0); PG8_STAGE(PG8_SA(0, 1), a2 + hstepA, voffA);
;             PG8_WAIT_V(8); PG8_WAIT_L(0); PG8_BAR; PG8_MMA(0, 0, At, B0); PG8_MMA(0, 1, At, B1); PG8_BAR; PG8_SCHED;
;             PG8_LDA(At, 1, 1); PG8_STAGE(PG8_SB(1, 0), b3, voffB); PG8_STAGE(PG8_SB(1, 1), b3 + hstepB, voffB); PG8_STAGE(PG8_SA(1, 0), a3, voffA);
;             PG8_WAIT_V(8); PG8_WAIT_L(0); PG8_BAR; PG8_MMA(1, 0, At, B0); PG8_MMA(1, 1, At, B1); PG8_BAR; PG8_SCHED;
	s_add_i32 s81, 0, 0x18000
	s_add_i32 s82, 0, 0x1c000
	v_add_u32_e32 v6, s81, v184
	v_add_u32_e32 v14, s81, v185
	v_add_u32_e32 v22, s82, v184
	v_add_u32_e32 v30, s82, v185
	ds_read_b128 v[2:5], v6
	ds_read_b128 v[10:13], v6 offset:2048
	ds_read_b128 v[6:9], v14
	ds_read_b128 v[14:17], v14 offset:2048
	ds_read_b128 v[18:21], v22
	ds_read_b128 v[26:29], v22 offset:2048
	ds_read_b128 v[22:25], v30
	ds_read_b128 v[30:33], v30 offset:2048
	s_add_u32 s58, s58, 0x40000
	s_addc_u32 s59, s59, 0
	s_mov_b32 m0, s62
	ds_read_b128 v[194:197], v191 offset:32768
	ds_read_b128 v[202:205], v191 offset:34816
	ds_read_b128 v[198:201], v192 offset:32768
	ds_read_b128 v[206:209], v192 offset:34816
	ds_read_b128 v[210:213], v191 offset:36864
	ds_read_b128 v[218:221], v191 offset:38912
	ds_read_b128 v[214:217], v192 offset:36864
	ds_read_b128 v[222:225], v192 offset:38912
	global_load_lds_dwordx4 v162, s[58:59]
	s_mov_b32 m0, s63
	s_nop 0
	global_load_lds_dwordx4 v166, s[58:59]
	s_waitcnt vmcnt(8)
	s_waitcnt lgkmcnt(0)
	s_barrier
	s_setprio 1
	s_waitcnt lgkmcnt(0)
	v_mfma_scale_f32_16x16x128_f8f6f4 v[158:161], v[2:9], v[194:201], v[158:161], v1, v182 op_sel_hi:[0,0,0]
	v_mfma_scale_f32_16x16x128_f8f6f4 v[154:157], v[10:17], v[194:201], v[154:157], v1, v182 op_sel_hi:[0,0,0]
	v_mfma_scale_f32_16x16x128_f8f6f4 v[150:153], v[2:9], v[202:209], v[150:153], v1, v182 op_sel_hi:[0,0,0]
	v_mfma_scale_f32_16x16x128_f8f6f4 v[138:141], v[10:17], v[202:209], v[138:141], v1, v182 op_sel_hi:[0,0,0]
	v_mfma_scale_f32_16x16x128_f8f6f4 v[130:133], v[2:9], v[210:217], v[130:133], v1, v182 op_sel_hi:[0,0,0]
	v_mfma_scale_f32_16x16x128_f8f6f4 v[122:125], v[10:17], v[210:217], v[122:125], v1, v182 op_sel_hi:[0,0,0]
	v_mfma_scale_f32_16x16x128_f8f6f4 v[118:121], v[2:9], v[218:225], v[118:121], v1, v182 op_sel_hi:[0,0,0]
	v_mfma_scale_f32_16x16x128_f8f6f4 v[106:109], v[10:17], v[218:225], v[106:109], v1, v182 op_sel_hi:[0,0,0]
	s_setprio 0
	s_setprio 1
	v_mfma_scale_f32_16x16x128_f8f6f4 v[146:149], v[18:25], v[194:201], v[146:149], v1, v182 op_sel_hi:[0,0,0]
	v_mfma_scale_f32_16x16x128_f8f6f4 v[142:145], v[26:33], v[194:201], v[142:145], v1, v182 op_sel_hi:[0,0,0]
	v_mfma_scale_f32_16x16x128_f8f6f4 v[134:137], v[18:25], v[202:209], v[134:137], v1, v182 op_sel_hi:[0,0,0]
	v_mfma_scale_f32_16x16x128_f8f6f4 v[126:129], v[26:33], v[202:209], v[126:129], v1, v182 op_sel_hi:[0,0,0]
	v_mfma_scale_f32_16x16x128_f8f6f4 v[114:117], v[18:25], v[210:217], v[114:117], v1, v182 op_sel_hi:[0,0,0]
	v_mfma_scale_f32_16x16x128_f8f6f4 v[110:113], v[26:33], v[210:217], v[110:113], v1, v182 op_sel_hi:[0,0,0]
	v_mfma_scale_f32_16x16x128_f8f6f4 v[102:105], v[18:25], v[218:225], v[102:105], v1, v182 op_sel_hi:[0,0,0]
	v_mfma_scale_f32_16x16x128_f8f6f4 v[98:101], v[26:33], v[218:225], v[98:101], v1, v182 op_sel_hi:[0,0,0]
	s_setprio 0
	s_barrier
	s_add_i32 s101, s81, s61
	s_add_u32 s98, s34, s10
	s_addc_u32 s99, s35, s11
	s_mov_b32 m0, s101
	ds_read_b128 v[194:197], v191 offset:49152
	ds_read_b128 v[202:205], v191 offset:51200
	ds_read_b128 v[198:201], v192 offset:49152
	ds_read_b128 v[206:209], v192 offset:51200
	ds_read_b128 v[210:213], v191 offset:53248
	ds_read_b128 v[218:221], v191 offset:55296
	ds_read_b128 v[214:217], v192 offset:53248
	ds_read_b128 v[222:225], v192 offset:55296
	global_load_lds_dwordx4 v164, s[98:99]
	s_add_i32 m0, s101, 0x2000
	s_add_u32 s34, s34, 0x40080
	s_addc_u32 s35, s35, 0
	s_add_i32 s101, s82, s61
	global_load_lds_dwordx4 v168, s[98:99]
	s_add_u32 s98, s58, s10
	s_addc_u32 s99, s59, s11
	s_sub_u32 s98, s98, 0x40000
	s_subb_u32 s99, s99, 0
	s_mov_b32 m0, s101
	s_nop 0
	global_load_lds_dwordx4 v164, s[34:35]
	s_add_i32 m0, s101, 0x2000
	s_nop 0
	global_load_lds_dwordx4 v168, s[34:35]
	s_mov_b32 m0, s69
	s_nop 0
	global_load_lds_dwordx4 v162, s[98:99]
	s_mov_b32 m0, s70
	s_nop 0
	global_load_lds_dwordx4 v166, s[98:99]
	s_waitcnt vmcnt(8)
	s_waitcnt lgkmcnt(0)
	s_barrier
	s_setprio 1
	s_waitcnt lgkmcnt(0)
	v_mfma_scale_f32_16x16x128_f8f6f4 v[94:97], v[2:9], v[194:201], v[94:97], v1, v182 op_sel_hi:[0,0,0]
	v_mfma_scale_f32_16x16x128_f8f6f4 v[90:93], v[10:17], v[194:201], v[90:93], v1, v182 op_sel_hi:[0,0,0]
	v_mfma_scale_f32_16x16x128_f8f6f4 v[82:85], v[2:9], v[202:209], v[82:85], v1, v182 op_sel_hi:[0,0,0]
	v_mfma_scale_f32_16x16x128_f8f6f4 v[74:77], v[10:17], v[202:209], v[74:77], v1, v182 op_sel_hi:[0,0,0]
	v_mfma_scale_f32_16x16x128_f8f6f4 v[66:69], v[2:9], v[210:217], v[66:69], v1, v182 op_sel_hi:[0,0,0]
	v_mfma_scale_f32_16x16x128_f8f6f4 v[58:61], v[10:17], v[210:217], v[58:61], v1, v182 op_sel_hi:[0,0,0]
	v_mfma_scale_f32_16x16x128_f8f6f4 v[50:53], v[2:9], v[218:225], v[50:53], v1, v182 op_sel_hi:[0,0,0]
	v_mfma_scale_f32_16x16x128_f8f6f4 v[42:45], v[10:17], v[218:225], v[42:45], v1, v182 op_sel_hi:[0,0,0]
	s_setprio 0
	s_setprio 1
	v_mfma_scale_f32_16x16x128_f8f6f4 v[86:89], v[18:25], v[194:201], v[86:89], v1, v182 op_sel_hi:[0,0,0]
	v_mfma_scale_f32_16x16x128_f8f6f4 v[78:81], v[26:33], v[194:201], v[78:81], v1, v182 op_sel_hi:[0,0,0]
	v_mfma_scale_f32_16x16x128_f8f6f4 v[70:73], v[18:25], v[202:209], v[70:73], v1, v182 op_sel_hi:[0,0,0]
	v_mfma_scale_f32_16x16x128_f8f6f4 v[62:65], v[26:33], v[202:209], v[62:65], v1, v182 op_sel_hi:[0,0,0]
	v_mfma_scale_f32_16x16x128_f8f6f4 v[54:57], v[18:25], v[210:217], v[54:57], v1, v182 op_sel_hi:[0,0,0]
	v_mfma_scale_f32_16x16x128_f8f6f4 v[46:49], v[26:33], v[210:217], v[46:49], v1, v182 op_sel_hi:[0,0,0]
	v_mfma_scale_f32_16x16x128_f8f6f4 v[38:41], v[18:25], v[218:225], v[38:41], v1, v182 op_sel_hi:[0,0,0]
	v_mfma_scale_f32_16x16x128_f8f6f4 v[34:37], v[26:33], v[218:225], v[34:37], v1, v182 op_sel_hi:[0,0,0]
	s_setprio 0
	s_barrier
	s_add_u32 s56, s56, 0x100
	s_addc_u32 s57, s57, 0
	s_add_u32 s78, s78, 0x100
	s_addc_u32 s79, s79, 0
	s_cmp_ge_u32 s80, s76
	s_mov_b32 s58, s80
	.p2align	6

; #define PG8_STAGE(bufoff, gbase, voff) do { _Pragma("unroll") for (int _i = 0; _i < 2; ++_i) \
;         __builtin_amdgcn_global_load_lds((const unsigned*)((const char*)(gbase) + (voff)[_i]), (PG8_LAS unsigned*)(lds + (bufoff) + ldsw + _i * 8192), 16, 0, 0); } while (0)
; #define PG8_LDA(dst, b, h) do { _Pragma("unroll") for (int m = 0; m < 4; ++m) _Pragma("unroll") for (int k = 0; k < 2; ++k) dst[m][k] = *(const PG8_LAS bf16x8*)(lds + PG8_SA(b, h) + aoff + m * 2048 + k * 1024); } while (0)
; #define PG8_LDB(dst, b, h) do { _Pragma("unroll") for (int n = 0; n < 2; ++n) _Pragma("unroll") for (int k = 0; k < 2; ++k) dst[n][k] = *(const PG8_LAS bf16x8*)(lds + PG8_SB(b, h) + boff + n * 2048 + k * 1024); } while (0)
; #define PG8_WAIT_V(n) asm volatile("s_waitcnt vmcnt(" #n ")" ::: "memory")
; #define PG8_WAIT_L(n) asm volatile("s_waitcnt lgkmcnt(" #n ")" ::: "memory")
; template <class Epi, class Sched, bool ALIGN_EPI = false>
; __device__ __forceinline__ void gemm_phase8(PG8_LAS unsigned char* lds, const Gemm g, const Sched& S, const Epi& E) {
;     ...
;         const bool has_next = S.next(ui + 1, nxt);
;         const size_t nko = (has_next && nxt.kp > 0) ? (size_t)nxt.kp * g.kpiece : 0;
;         const char* nA = has_next ? (const char*)g.A + (size_t)nxt.pm * tstepA + (size_t)nxt.pn * astep + nko : cA; const char* nB = has_next ? (const char*)g.Bt + (size_t)nxt.pn * tstepB + nko : cB;
;         const int nt = (cur.kp < 0 ? g.K : g.kpiece) / 128;
;         for (int t = 0; t < nt; t += 2) {
;             const bool last = (t == nt - 2);
;             const char* a1 = cA + (size_t)(t + 1) * kstep;
;             const char* a2 = last ? nA : cA + (size_t)(t + 2) * kstep; const char* b2 = last ? nB : cB + (size_t)(t + 2) * kstep;
;             const char* a3 = a2 + kstep; const char* b3 = b2 + kstep;
;             if (last && has_next) S.a_ready(nxt);
;             PG8_LDB(B0, 0, 0); PG8_LDB(B1, 0, 1); PG8_SCHED; PG8_LDA(At, 0, 0); PG8_STAGE(PG8_SA(1, 1), a1 + hstepA, voffA);
;             PG8_WAIT_V(8); PG8_WAIT_L(0); PG8_BAR; PG8_MMA(0, 0, At, B0); PG8_MMA(0, 1, At, B1); PG8_BAR; PG8_SCHED;
;             PG8_LDA(At, 0, 1); PG8_STAGE(PG8_SB(0, 0), b2, voffB); PG8_STAGE(PG8_SB(0, 1), b2 + hstepB, voffB); PG8_STAGE(PG8_SA(0, 0), a2, voffA);
;             PG8_WAIT_V(8); PG8_WAIT_L(0); PG8_BAR; PG8_MMA(1, 0, At, B0); PG8_MMA(1, 1, At, B1); PG8_BAR; PG8_SCHED;
.LBB0_1421:
	s_ashr_i32 s13, s12, 31
	s_lshl_b64 s[14:15], s[12:13], 19
	s_add_u32 s14, s26, s14
	s_addc_u32 s15, s27, s15
	s_and_b64 s[16:17], s[2:3], exec
	s_cselect_b32 s13, s15, s21
	s_cselect_b32 s45, s14, s20
	s_ashr_i32 s11, s10, 31
	s_lshl_b64 s[16:17], s[10:11], 19
	s_add_u32 s16, s28, s16
	s_addc_u32 s17, s29, s17
	s_and_b64 s[24:25], s[2:3], exec
	s_cselect_b32 s11, s17, s23
	s_cselect_b32 s52, s16, s22
	s_add_u32 s20, s20, 0x40080
	s_addc_u32 s21, s21, 0
	s_add_u32 s53, s22, 0x100
	s_addc_u32 s54, s23, 0
	s_mov_b32 s55, -2
	ds_read_b128 v[18:21], v191
	ds_read_b128 v[26:29], v191 offset:2048
	ds_read_b128 v[22:25], v192
	ds_read_b128 v[30:33], v192 offset:2048
	ds_read_b128 v[2:5], v193
	ds_read_b128 v[10:13], v193 offset:2048
	ds_read_b128 v[6:9], v194
	ds_read_b128 v[14:17], v194 offset:2048
	s_add_u32 s22, s20, 0xfffc0080
	s_addc_u32 s23, s21, -1
	s_cmp_eq_u32 s55, 12
	s_cselect_b32 s25, s13, s23
	s_cselect_b32 s24, s45, s22
	s_cselect_b32 s23, s11, s54
	s_cselect_b32 s22, s52, s53
	s_add_i32 m0, s19, 0xc000
	ds_read_b128 v[178:181], v195
	ds_read_b128 v[198:201], v195 offset:2048
	ds_read_b128 v[182:185], v196
	ds_read_b128 v[202:205], v196 offset:2048
	ds_read_b128 v[206:209], v195 offset:4096
	ds_read_b128 v[214:217], v195 offset:6144
	ds_read_b128 v[210:213], v196 offset:4096
	ds_read_b128 v[218:221], v196 offset:6144
	global_load_lds_dwordx4 v170, s[20:21]
	s_add_i32 m0, s19, 0xe000
	s_nop 0
	global_load_lds_dwordx4 v172, s[20:21]
	s_waitcnt vmcnt(8)
	s_waitcnt lgkmcnt(0)
	s_barrier
	s_setprio 1
	s_waitcnt lgkmcnt(0)
	v_mfma_scale_f32_16x16x128_f8f6f4 v[158:161], v[18:25], v[178:185], 0, v1, v186 op_sel_hi:[0,0,0]
	v_mfma_scale_f32_16x16x128_f8f6f4 v[150:153], v[26:33], v[178:185], 0, v1, v186 op_sel_hi:[0,0,0]
	v_mfma_scale_f32_16x16x128_f8f6f4 v[142:145], v[18:25], v[198:205], 0, v1, v186 op_sel_hi:[0,0,0]
	v_mfma_scale_f32_16x16x128_f8f6f4 v[134:137], v[26:33], v[198:205], 0, v1, v186 op_sel_hi:[0,0,0]
	v_mfma_scale_f32_16x16x128_f8f6f4 v[126:129], v[18:25], v[206:213], 0, v1, v186 op_sel_hi:[0,0,0]
	v_mfma_scale_f32_16x16x128_f8f6f4 v[118:121], v[26:33], v[206:213], 0, v1, v186 op_sel_hi:[0,0,0]
	v_mfma_scale_f32_16x16x128_f8f6f4 v[110:113], v[18:25], v[214:221], 0, v1, v186 op_sel_hi:[0,0,0]
	v_mfma_scale_f32_16x16x128_f8f6f4 v[102:105], v[26:33], v[214:221], 0, v1, v186 op_sel_hi:[0,0,0]
	s_setprio 0
	s_setprio 1
	v_mfma_scale_f32_16x16x128_f8f6f4 v[154:157], v[2:9], v[178:185], 0, v1, v186 op_sel_hi:[0,0,0]
	v_mfma_scale_f32_16x16x128_f8f6f4 v[146:149], v[10:17], v[178:185], 0, v1, v186 op_sel_hi:[0,0,0]
	v_mfma_scale_f32_16x16x128_f8f6f4 v[138:141], v[2:9], v[198:205], 0, v1, v186 op_sel_hi:[0,0,0]
	v_mfma_scale_f32_16x16x128_f8f6f4 v[130:133], v[10:17], v[198:205], 0, v1, v186 op_sel_hi:[0,0,0]
	v_mfma_scale_f32_16x16x128_f8f6f4 v[122:125], v[2:9], v[206:213], 0, v1, v186 op_sel_hi:[0,0,0]
	v_mfma_scale_f32_16x16x128_f8f6f4 v[114:117], v[10:17], v[206:213], 0, v1, v186 op_sel_hi:[0,0,0]
	v_mfma_scale_f32_16x16x128_f8f6f4 v[106:109], v[2:9], v[214:221], 0, v1, v186 op_sel_hi:[0,0,0]
	v_mfma_scale_f32_16x16x128_f8f6f4 v[98:101], v[10:17], v[214:221], 0, v1, v186 op_sel_hi:[0,0,0]
	s_setprio 0
	s_barrier
	s_add_i32 s56, s41, s30
	s_mov_b32 m0, s56
	ds_read_b128 v[198:201], v195 offset:16384
	ds_read_b128 v[206:209], v195 offset:18432
	ds_read_b128 v[202:205], v196 offset:16384
	ds_read_b128 v[210:213], v196 offset:18432
	ds_read_b128 v[214:217], v195 offset:20480
	ds_read_b128 v[222:225], v195 offset:22528
	ds_read_b128 v[218:221], v196 offset:20480
	ds_read_b128 v[226:229], v196 offset:22528
	global_load_lds_dwordx4 v164, s[22:23]
	s_add_i32 m0, s56, 0x2000
	s_add_u32 s56, s22, 0x40000
	s_addc_u32 s57, s23, 0
	s_add_i32 s58, s42, s30
	global_load_lds_dwordx4 v168, s[22:23]
	s_mov_b32 m0, s58
	s_nop 0
	global_load_lds_dwordx4 v164, s[56:57]
	s_add_i32 m0, s58, 0x2000
	s_nop 0
	global_load_lds_dwordx4 v168, s[56:57]
	s_mov_b32 m0, s19
	s_nop 0
	global_load_lds_dwordx4 v162, s[24:25]
	s_mov_b32 m0, s34
	s_nop 0
	global_load_lds_dwordx4 v166, s[24:25]
	s_waitcnt vmcnt(8)
	s_waitcnt lgkmcnt(0)
	s_barrier
	s_setprio 1
	s_waitcnt lgkmcnt(0)
	v_mfma_scale_f32_16x16x128_f8f6f4 v[94:97], v[18:25], v[198:205], 0, v1, v186 op_sel_hi:[0,0,0]
	v_mfma_scale_f32_16x16x128_f8f6f4 v[86:89], v[26:33], v[198:205], 0, v1, v186 op_sel_hi:[0,0,0]
	v_mfma_scale_f32_16x16x128_f8f6f4 v[78:81], v[18:25], v[206:213], 0, v1, v186 op_sel_hi:[0,0,0]
	v_mfma_scale_f32_16x16x128_f8f6f4 v[70:73], v[26:33], v[206:213], 0, v1, v186 op_sel_hi:[0,0,0]
	v_mfma_scale_f32_16x16x128_f8f6f4 v[62:65], v[18:25], v[214:221], 0, v1, v186 op_sel_hi:[0,0,0]
	v_mfma_scale_f32_16x16x128_f8f6f4 v[54:57], v[26:33], v[214:221], 0, v1, v186 op_sel_hi:[0,0,0]
	v_mfma_scale_f32_16x16x128_f8f6f4 v[46:49], v[18:25], v[222:229], 0, v1, v186 op_sel_hi:[0,0,0]
	v_mfma_scale_f32_16x16x128_f8f6f4 v[38:41], v[26:33], v[222:229], 0, v1, v186 op_sel_hi:[0,0,0]
	s_setprio 0
	s_setprio 1
	v_mfma_scale_f32_16x16x128_f8f6f4 v[90:93], v[2:9], v[198:205], 0, v1, v186 op_sel_hi:[0,0,0]
	v_mfma_scale_f32_16x16x128_f8f6f4 v[82:85], v[10:17], v[198:205], 0, v1, v186 op_sel_hi:[0,0,0]
	v_mfma_scale_f32_16x16x128_f8f6f4 v[74:77], v[2:9], v[206:213], 0, v1, v186 op_sel_hi:[0,0,0]
	v_mfma_scale_f32_16x16x128_f8f6f4 v[66:69], v[10:17], v[206:213], 0, v1, v186 op_sel_hi:[0,0,0]
	v_mfma_scale_f32_16x16x128_f8f6f4 v[58:61], v[2:9], v[214:221], 0, v1, v186 op_sel_hi:[0,0,0]
	v_mfma_scale_f32_16x16x128_f8f6f4 v[50:53], v[10:17], v[214:221], 0, v1, v186 op_sel_hi:[0,0,0]
	v_mfma_scale_f32_16x16x128_f8f6f4 v[42:45], v[2:9], v[222:229], 0, v1, v186 op_sel_hi:[0,0,0]
	v_mfma_scale_f32_16x16x128_f8f6f4 v[34:37], v[10:17], v[222:229], 0, v1, v186 op_sel_hi:[0,0,0]
	s_setprio 0
	s_barrier
; #define PG8_STAGE(bufoff, gbase, voff) do { _Pragma("unroll") for (int _i = 0; _i < 2; ++_i) \
;         __builtin_amdgcn_global_load_lds((const unsigned*)((const char*)(gbase) + (voff)[_i]), (PG8_LAS unsigned*)(lds + (bufoff) + ldsw + _i * 8192), 16, 0, 0); } while (0)
; #define PG8_LDA(dst, b, h) do { _Pragma("unroll") for (int m = 0; m < 4; ++m) _Pragma("unroll") for (int k = 0; k < 2; ++k) dst[m][k] = *(const PG8_LAS bf16x8*)(lds + PG8_SA(b, h) + aoff + m * 2048 + k * 1024); } while (0)
; #define PG8_LDB(dst, b, h) do { _Pragma("unroll") for (int n = 0; n < 2; ++n) _Pragma("unroll") for (int k = 0; k < 2; ++k) dst[n][k] = *(const PG8_LAS bf16x8*)(lds + PG8_SB(b, h) + boff + n * 2048 + k * 1024); } while (0)
; #define PG8_BAR __builtin_amdgcn_s_barrier()
; template <class Epi, class Sched, bool ALIGN_EPI = false>
; __device__ __forceinline__ void gemm_phase8(PG8_LAS unsigned char* lds, const Gemm g, const Sched& S, const Epi& E) {
;     ...
;         for (int t = 0; t < nt; t += 2) {
;             const bool last = (t == nt - 2);
;             const char* a1 = cA + (size_t)(t + 1) * kstep;
;             const char* a2 = last ? nA : cA + (size_t)(t + 2) * kstep; const char* b2 = last ? nB : cB + (size_t)(t + 2) * kstep;
;             const char* a3 = a2 + kstep; const char* b3 = b2 + kstep;
;             if (last && has_next) S.a_ready(nxt);
;             PG8_LDB(B0, 0, 0); PG8_LDB(B1, 0, 1); PG8_SCHED; PG8_LDA(At, 0, 0); PG8_STAGE(PG8_SA(1, 1), a1 + hstepA, voffA);
;             PG8_WAIT_V(8); PG8_WAIT_L(0); PG8_BAR; PG8_MMA(0, 0, At, B0); PG8_MMA(0, 1, At, B1); PG8_BAR; PG8_SCHED;
;             PG8_LDA(At, 0, 1); PG8_STAGE(PG8_SB(0, 0), b2, voffB); PG8_STAGE(PG8_SB(0, 1), b2 + hstepB, voffB); PG8_STAGE(PG8_SA(0, 0), a2, voffA);
;             PG8_WAIT_V(8); PG8_WAIT_L(0); PG8_BAR; PG8_MMA(1, 0, At, B0); PG8_MMA(1, 1, At, B1); PG8_BAR; PG8_SCHED;
;             PG8_LDB(B0, 1, 0); PG8_LDB(B1, 1, 1); PG8_SCHED; PG8_LDA(At, 1, 0); PG8_STAGE(PG8_SA(0, 1), a2 + hstepA, voffA);
;             PG8_WAIT_V(8); PG8_WAIT_L(0); PG8_BAR; PG8_MMA(0, 0, At, B0); PG8_MMA(0, 1, At, B1); PG8_BAR; PG8_SCHED;
;             PG8_LDA(At, 1, 1); PG8_STAGE(PG8_SB(1, 0), b3, voffB); PG8_STAGE(PG8_SB(1, 1), b3 + hstepB, voffB); PG8_STAGE(PG8_SA(1, 0), a3, voffA);
;             PG8_WAIT_V(8); PG8_WAIT_L(0); PG8_BAR; PG8_MMA(1, 0, At, B0); PG8_MMA(1, 1, At, B1); PG8_BAR; PG8_SCHED;
	s_add_i32 s56, 0, 0x18000
	s_add_i32 s57, 0, 0x1c000
	v_add_u32_e32 v6, s56, v187
	v_add_u32_e32 v14, s56, v188
	v_add_u32_e32 v22, s57, v187
	v_add_u32_e32 v30, s57, v188
	ds_read_b128 v[2:5], v6
	ds_read_b128 v[10:13], v6 offset:2048
	ds_read_b128 v[6:9], v14
	ds_read_b128 v[14:17], v14 offset:2048
	ds_read_b128 v[18:21], v22
	ds_read_b128 v[26:29], v22 offset:2048
	ds_read_b128 v[22:25], v30
	ds_read_b128 v[30:33], v30 offset:2048
	s_add_u32 s24, s24, 0x40000
	s_addc_u32 s25, s25, 0
	s_mov_b32 m0, s35
	ds_read_b128 v[198:201], v195 offset:32768
	ds_read_b128 v[206:209], v195 offset:34816
	ds_read_b128 v[202:205], v196 offset:32768
	ds_read_b128 v[210:213], v196 offset:34816
	ds_read_b128 v[214:217], v195 offset:36864
	ds_read_b128 v[222:225], v195 offset:38912
	ds_read_b128 v[218:221], v196 offset:36864
	ds_read_b128 v[226:229], v196 offset:38912
	global_load_lds_dwordx4 v162, s[24:25]
	s_mov_b32 m0, s36
	s_nop 0
	global_load_lds_dwordx4 v166, s[24:25]
	s_waitcnt vmcnt(8)
	s_waitcnt lgkmcnt(0)
	s_barrier
	s_setprio 1
	s_waitcnt lgkmcnt(0)
	v_mfma_scale_f32_16x16x128_f8f6f4 v[158:161], v[2:9], v[198:205], v[158:161], v1, v186 op_sel_hi:[0,0,0]
	v_mfma_scale_f32_16x16x128_f8f6f4 v[150:153], v[10:17], v[198:205], v[150:153], v1, v186 op_sel_hi:[0,0,0]
	v_mfma_scale_f32_16x16x128_f8f6f4 v[142:145], v[2:9], v[206:213], v[142:145], v1, v186 op_sel_hi:[0,0,0]
	v_mfma_scale_f32_16x16x128_f8f6f4 v[134:137], v[10:17], v[206:213], v[134:137], v1, v186 op_sel_hi:[0,0,0]
	v_mfma_scale_f32_16x16x128_f8f6f4 v[126:129], v[2:9], v[214:221], v[126:129], v1, v186 op_sel_hi:[0,0,0]
	v_mfma_scale_f32_16x16x128_f8f6f4 v[118:121], v[10:17], v[214:221], v[118:121], v1, v186 op_sel_hi:[0,0,0]
	v_mfma_scale_f32_16x16x128_f8f6f4 v[110:113], v[2:9], v[222:229], v[110:113], v1, v186 op_sel_hi:[0,0,0]
	v_mfma_scale_f32_16x16x128_f8f6f4 v[102:105], v[10:17], v[222:229], v[102:105], v1, v186 op_sel_hi:[0,0,0]
	s_setprio 0
	s_setprio 1
	v_mfma_scale_f32_16x16x128_f8f6f4 v[154:157], v[18:25], v[198:205], v[154:157], v1, v186 op_sel_hi:[0,0,0]
	v_mfma_scale_f32_16x16x128_f8f6f4 v[146:149], v[26:33], v[198:205], v[146:149], v1, v186 op_sel_hi:[0,0,0]
	v_mfma_scale_f32_16x16x128_f8f6f4 v[138:141], v[18:25], v[206:213], v[138:141], v1, v186 op_sel_hi:[0,0,0]
	v_mfma_scale_f32_16x16x128_f8f6f4 v[130:133], v[26:33], v[206:213], v[130:133], v1, v186 op_sel_hi:[0,0,0]
	v_mfma_scale_f32_16x16x128_f8f6f4 v[122:125], v[18:25], v[214:221], v[122:125], v1, v186 op_sel_hi:[0,0,0]
	v_mfma_scale_f32_16x16x128_f8f6f4 v[114:117], v[26:33], v[214:221], v[114:117], v1, v186 op_sel_hi:[0,0,0]
	v_mfma_scale_f32_16x16x128_f8f6f4 v[106:109], v[18:25], v[222:229], v[106:109], v1, v186 op_sel_hi:[0,0,0]
	v_mfma_scale_f32_16x16x128_f8f6f4 v[98:101], v[26:33], v[222:229], v[98:101], v1, v186 op_sel_hi:[0,0,0]
	s_setprio 0
	s_barrier
	s_add_i32 s101, s56, s30
	s_add_u32 s98, s22, s6
	s_addc_u32 s99, s23, s7
	s_mov_b32 m0, s101
	ds_read_b128 v[198:201], v195 offset:49152
	ds_read_b128 v[206:209], v195 offset:51200
	ds_read_b128 v[202:205], v196 offset:49152
	ds_read_b128 v[210:213], v196 offset:51200
	ds_read_b128 v[214:217], v195 offset:53248
	ds_read_b128 v[222:225], v195 offset:55296
	ds_read_b128 v[218:221], v196 offset:53248
	ds_read_b128 v[226:229], v196 offset:55296
	global_load_lds_dwordx4 v164, s[98:99]
	s_add_i32 m0, s101, 0x2000
	s_add_u32 s22, s22, 0x40080
	s_addc_u32 s23, s23, 0
	s_add_i32 s101, s57, s30
	global_load_lds_dwordx4 v168, s[98:99]
	s_add_u32 s98, s24, s6
	s_addc_u32 s99, s25, s7
	s_sub_u32 s98, s98, 0x40000
	s_subb_u32 s99, s99, 0
	s_mov_b32 m0, s101
	s_nop 0
	global_load_lds_dwordx4 v164, s[22:23]
	s_add_i32 m0, s101, 0x2000
	s_nop 0
	global_load_lds_dwordx4 v168, s[22:23]
	s_mov_b32 m0, s39
	s_nop 0
	global_load_lds_dwordx4 v162, s[98:99]
	s_mov_b32 m0, s40
	s_nop 0
	global_load_lds_dwordx4 v166, s[98:99]
	s_waitcnt vmcnt(8)
	s_waitcnt lgkmcnt(0)
	s_barrier
	s_setprio 1
	s_waitcnt lgkmcnt(0)
	v_mfma_scale_f32_16x16x128_f8f6f4 v[94:97], v[2:9], v[198:205], v[94:97], v1, v186 op_sel_hi:[0,0,0]
	v_mfma_scale_f32_16x16x128_f8f6f4 v[86:89], v[10:17], v[198:205], v[86:89], v1, v186 op_sel_hi:[0,0,0]
	v_mfma_scale_f32_16x16x128_f8f6f4 v[78:81], v[2:9], v[206:213], v[78:81], v1, v186 op_sel_hi:[0,0,0]
	v_mfma_scale_f32_16x16x128_f8f6f4 v[70:73], v[10:17], v[206:213], v[70:73], v1, v186 op_sel_hi:[0,0,0]
	v_mfma_scale_f32_16x16x128_f8f6f4 v[62:65], v[2:9], v[214:221], v[62:65], v1, v186 op_sel_hi:[0,0,0]
	v_mfma_scale_f32_16x16x128_f8f6f4 v[54:57], v[10:17], v[214:221], v[54:57], v1, v186 op_sel_hi:[0,0,0]
	v_mfma_scale_f32_16x16x128_f8f6f4 v[46:49], v[2:9], v[222:229], v[46:49], v1, v186 op_sel_hi:[0,0,0]
	v_mfma_scale_f32_16x16x128_f8f6f4 v[38:41], v[10:17], v[222:229], v[38:41], v1, v186 op_sel_hi:[0,0,0]
	s_setprio 0
	s_setprio 1
	v_mfma_scale_f32_16x16x128_f8f6f4 v[90:93], v[18:25], v[198:205], v[90:93], v1, v186 op_sel_hi:[0,0,0]
	v_mfma_scale_f32_16x16x128_f8f6f4 v[82:85], v[26:33], v[198:205], v[82:85], v1, v186 op_sel_hi:[0,0,0]
	v_mfma_scale_f32_16x16x128_f8f6f4 v[74:77], v[18:25], v[206:213], v[74:77], v1, v186 op_sel_hi:[0,0,0]
	v_mfma_scale_f32_16x16x128_f8f6f4 v[66:69], v[26:33], v[206:213], v[66:69], v1, v186 op_sel_hi:[0,0,0]
	v_mfma_scale_f32_16x16x128_f8f6f4 v[58:61], v[18:25], v[214:221], v[58:61], v1, v186 op_sel_hi:[0,0,0]
	v_mfma_scale_f32_16x16x128_f8f6f4 v[50:53], v[26:33], v[214:221], v[50:53], v1, v186 op_sel_hi:[0,0,0]
	v_mfma_scale_f32_16x16x128_f8f6f4 v[42:45], v[18:25], v[222:229], v[42:45], v1, v186 op_sel_hi:[0,0,0]
	v_mfma_scale_f32_16x16x128_f8f6f4 v[34:37], v[26:33], v[222:229], v[34:37], v1, v186 op_sel_hi:[0,0,0]
	s_setprio 0
	s_barrier
	s_add_i32 s55, s55, 2
	s_add_u32 s20, s20, 0x100
	s_addc_u32 s21, s21, 0
	s_add_u32 s53, s53, 0x100
	s_addc_u32 s54, s54, 0
	s_cmp_gt_u32 s55, 13
	.p2align	6

; #define PG8_STAGE(bufoff, gbase, voff) do { _Pragma("unroll") for (int _i = 0; _i < 2; ++_i) \
;         __builtin_amdgcn_global_load_lds((const unsigned*)((const char*)(gbase) + (voff)[_i]), (PG8_LAS unsigned*)(lds + (bufoff) + ldsw + _i * 8192), 16, 0, 0); } while (0)
; #define PG8_LDA(dst, b, h) do { _Pragma("unroll") for (int m = 0; m < 4; ++m) _Pragma("unroll") for (int k = 0; k < 2; ++k) dst[m][k] = *(const PG8_LAS bf16x8*)(lds + PG8_SA(b, h) + aoff + m * 2048 + k * 1024); } while (0)
; #define PG8_LDB(dst, b, h) do { _Pragma("unroll") for (int n = 0; n < 2; ++n) _Pragma("unroll") for (int k = 0; k < 2; ++k) dst[n][k] = *(const PG8_LAS bf16x8*)(lds + PG8_SB(b, h) + boff + n * 2048 + k * 1024); } while (0)
; #define PG8_WAIT_V(n) asm volatile("s_waitcnt vmcnt(" #n ")" ::: "memory")
; #define PG8_WAIT_L(n) asm volatile("s_waitcnt lgkmcnt(" #n ")" ::: "memory")
; template <class Epi, class Sched, bool ALIGN_EPI = false>
; __device__ __forceinline__ void gemm_phase8(PG8_LAS unsigned char* lds, const Gemm g, const Sched& S, const Epi& E) {
;     ...
;         const bool has_next = S.next(ui + 1, nxt);
;         const size_t nko = (has_next && nxt.kp > 0) ? (size_t)nxt.kp * g.kpiece : 0;
;         const char* nA = has_next ? (const char*)g.A + (size_t)nxt.pm * tstepA + (size_t)nxt.pn * astep + nko : cA; const char* nB = has_next ? (const char*)g.Bt + (size_t)nxt.pn * tstepB + nko : cB;
;         const int nt = (cur.kp < 0 ? g.K : g.kpiece) / 128;
;         for (int t = 0; t < nt; t += 2) {
;             const bool last = (t == nt - 2);
;             const char* a1 = cA + (size_t)(t + 1) * kstep;
;             const char* a2 = last ? nA : cA + (size_t)(t + 2) * kstep; const char* b2 = last ? nB : cB + (size_t)(t + 2) * kstep;
;             const char* a3 = a2 + kstep; const char* b3 = b2 + kstep;
;             if (last && has_next) S.a_ready(nxt);
;             PG8_LDB(B0, 0, 0); PG8_LDB(B1, 0, 1); PG8_SCHED; PG8_LDA(At, 0, 0); PG8_STAGE(PG8_SA(1, 1), a1 + hstepA, voffA);
;             PG8_WAIT_V(8); PG8_WAIT_L(0); PG8_BAR; PG8_MMA(0, 0, At, B0); PG8_MMA(0, 1, At, B1); PG8_BAR; PG8_SCHED;
;             PG8_LDA(At, 0, 1); PG8_STAGE(PG8_SB(0, 0), b2, voffB); PG8_STAGE(PG8_SB(0, 1), b2 + hstepB, voffB); PG8_STAGE(PG8_SA(0, 0), a2, voffA);
;             PG8_WAIT_V(8); PG8_WAIT_L(0); PG8_BAR; PG8_MMA(1, 0, At, B0); PG8_MMA(1, 1, At, B1); PG8_BAR; PG8_SCHED;
.LBB0_1510:
	s_cmp_gt_i32 s30, -1
	s_cselect_b64 s[36:37], -1, 0
	s_cmp_lt_i32 s30, 0
	s_cselect_b32 s31, 44, 4
	s_add_i32 s79, s31, -2
	s_add_u32 s38, s38, 0xb0080
	s_addc_u32 s39, s39, 0
	s_add_u32 s80, s34, 0x100
	s_mov_b32 s40, 0
	s_addc_u32 s81, s35, 0
	ds_read_b128 v[18:21], v187
	ds_read_b128 v[26:29], v187 offset:2048
	ds_read_b128 v[22:25], v188
	ds_read_b128 v[30:33], v188 offset:2048
	ds_read_b128 v[2:5], v189
	ds_read_b128 v[10:13], v189 offset:2048
	ds_read_b128 v[6:9], v190
	ds_read_b128 v[14:17], v190 offset:2048
	s_add_i32 s82, s40, 2
	s_add_u32 s34, s38, 0xfff50080
	s_addc_u32 s35, s39, -1
	s_cmp_eq_u32 s79, s40
	s_cselect_b32 s40, s26, s34
	s_cselect_b32 s41, s27, s35
	s_cselect_b32 s35, s29, s81
	s_cselect_b32 s34, s28, s80
	s_add_i32 m0, s52, 0xc000
	ds_read_b128 v[174:177], v191
	ds_read_b128 v[194:197], v191 offset:2048
	ds_read_b128 v[178:181], v192
	ds_read_b128 v[198:201], v192 offset:2048
	ds_read_b128 v[202:205], v191 offset:4096
	ds_read_b128 v[210:213], v191 offset:6144
	ds_read_b128 v[206:209], v192 offset:4096
	ds_read_b128 v[214:217], v192 offset:6144
	global_load_lds_dwordx4 v170, s[38:39]
	s_add_i32 m0, s52, 0xe000
	s_nop 0
	global_load_lds_dwordx4 v172, s[38:39]
	s_waitcnt vmcnt(8)
	s_waitcnt lgkmcnt(0)
	s_barrier
	s_setprio 1
	s_waitcnt lgkmcnt(0)
	v_mfma_scale_f32_16x16x128_f8f6f4 v[158:161], v[18:25], v[174:181], 0, v1, v182 op_sel_hi:[0,0,0]
	v_mfma_scale_f32_16x16x128_f8f6f4 v[154:157], v[26:33], v[174:181], 0, v1, v182 op_sel_hi:[0,0,0]
	v_mfma_scale_f32_16x16x128_f8f6f4 v[150:153], v[18:25], v[194:201], 0, v1, v182 op_sel_hi:[0,0,0]
	v_mfma_scale_f32_16x16x128_f8f6f4 v[138:141], v[26:33], v[194:201], 0, v1, v182 op_sel_hi:[0,0,0]
	v_mfma_scale_f32_16x16x128_f8f6f4 v[130:133], v[18:25], v[202:209], 0, v1, v182 op_sel_hi:[0,0,0]
	v_mfma_scale_f32_16x16x128_f8f6f4 v[122:125], v[26:33], v[202:209], 0, v1, v182 op_sel_hi:[0,0,0]
	v_mfma_scale_f32_16x16x128_f8f6f4 v[118:121], v[18:25], v[210:217], 0, v1, v182 op_sel_hi:[0,0,0]
	v_mfma_scale_f32_16x16x128_f8f6f4 v[106:109], v[26:33], v[210:217], 0, v1, v182 op_sel_hi:[0,0,0]
	s_setprio 0
	s_setprio 1
	v_mfma_scale_f32_16x16x128_f8f6f4 v[146:149], v[2:9], v[174:181], 0, v1, v182 op_sel_hi:[0,0,0]
	v_mfma_scale_f32_16x16x128_f8f6f4 v[142:145], v[10:17], v[174:181], 0, v1, v182 op_sel_hi:[0,0,0]
	v_mfma_scale_f32_16x16x128_f8f6f4 v[134:137], v[2:9], v[194:201], 0, v1, v182 op_sel_hi:[0,0,0]
	v_mfma_scale_f32_16x16x128_f8f6f4 v[126:129], v[10:17], v[194:201], 0, v1, v182 op_sel_hi:[0,0,0]
	v_mfma_scale_f32_16x16x128_f8f6f4 v[114:117], v[2:9], v[202:209], 0, v1, v182 op_sel_hi:[0,0,0]
	v_mfma_scale_f32_16x16x128_f8f6f4 v[110:113], v[10:17], v[202:209], 0, v1, v182 op_sel_hi:[0,0,0]
	v_mfma_scale_f32_16x16x128_f8f6f4 v[102:105], v[2:9], v[210:217], 0, v1, v182 op_sel_hi:[0,0,0]
	v_mfma_scale_f32_16x16x128_f8f6f4 v[98:101], v[10:17], v[210:217], 0, v1, v182 op_sel_hi:[0,0,0]
	s_setprio 0
	s_barrier
	s_add_i32 s83, s63, s45
	s_mov_b32 m0, s83
	ds_read_b128 v[194:197], v191 offset:16384
	ds_read_b128 v[202:205], v191 offset:18432
	ds_read_b128 v[198:201], v192 offset:16384
	ds_read_b128 v[206:209], v192 offset:18432
	ds_read_b128 v[210:213], v191 offset:20480
	ds_read_b128 v[218:221], v191 offset:22528
	ds_read_b128 v[214:217], v192 offset:20480
	ds_read_b128 v[222:225], v192 offset:22528
	global_load_lds_dwordx4 v164, s[34:35]
	s_add_i32 m0, s83, 0x2000
	s_add_u32 s84, s34, 0xb0000
	s_addc_u32 s85, s35, 0
	s_add_i32 s83, s64, s45
	global_load_lds_dwordx4 v168, s[34:35]
	s_mov_b32 m0, s83
	s_nop 0
	global_load_lds_dwordx4 v164, s[84:85]
	s_add_i32 m0, s83, 0x2000
	s_nop 0
	global_load_lds_dwordx4 v168, s[84:85]
	s_mov_b32 m0, s52
	s_nop 0
	global_load_lds_dwordx4 v162, s[40:41]
	s_mov_b32 m0, s53
	s_nop 0
	global_load_lds_dwordx4 v166, s[40:41]
	s_waitcnt vmcnt(8)
	s_waitcnt lgkmcnt(0)
	s_barrier
	s_setprio 1
	s_waitcnt lgkmcnt(0)
	v_mfma_scale_f32_16x16x128_f8f6f4 v[94:97], v[18:25], v[194:201], 0, v1, v182 op_sel_hi:[0,0,0]
	v_mfma_scale_f32_16x16x128_f8f6f4 v[90:93], v[26:33], v[194:201], 0, v1, v182 op_sel_hi:[0,0,0]
	v_mfma_scale_f32_16x16x128_f8f6f4 v[82:85], v[18:25], v[202:209], 0, v1, v182 op_sel_hi:[0,0,0]
	v_mfma_scale_f32_16x16x128_f8f6f4 v[74:77], v[26:33], v[202:209], 0, v1, v182 op_sel_hi:[0,0,0]
	v_mfma_scale_f32_16x16x128_f8f6f4 v[66:69], v[18:25], v[210:217], 0, v1, v182 op_sel_hi:[0,0,0]
	v_mfma_scale_f32_16x16x128_f8f6f4 v[58:61], v[26:33], v[210:217], 0, v1, v182 op_sel_hi:[0,0,0]
	v_mfma_scale_f32_16x16x128_f8f6f4 v[50:53], v[18:25], v[218:225], 0, v1, v182 op_sel_hi:[0,0,0]
	v_mfma_scale_f32_16x16x128_f8f6f4 v[42:45], v[26:33], v[218:225], 0, v1, v182 op_sel_hi:[0,0,0]
	s_setprio 0
	s_setprio 1
	v_mfma_scale_f32_16x16x128_f8f6f4 v[86:89], v[2:9], v[194:201], 0, v1, v182 op_sel_hi:[0,0,0]
	v_mfma_scale_f32_16x16x128_f8f6f4 v[78:81], v[10:17], v[194:201], 0, v1, v182 op_sel_hi:[0,0,0]
	v_mfma_scale_f32_16x16x128_f8f6f4 v[70:73], v[2:9], v[202:209], 0, v1, v182 op_sel_hi:[0,0,0]
	v_mfma_scale_f32_16x16x128_f8f6f4 v[62:65], v[10:17], v[202:209], 0, v1, v182 op_sel_hi:[0,0,0]
	v_mfma_scale_f32_16x16x128_f8f6f4 v[54:57], v[2:9], v[210:217], 0, v1, v182 op_sel_hi:[0,0,0]
	v_mfma_scale_f32_16x16x128_f8f6f4 v[46:49], v[10:17], v[210:217], 0, v1, v182 op_sel_hi:[0,0,0]
	v_mfma_scale_f32_16x16x128_f8f6f4 v[38:41], v[2:9], v[218:225], 0, v1, v182 op_sel_hi:[0,0,0]
	v_mfma_scale_f32_16x16x128_f8f6f4 v[34:37], v[10:17], v[218:225], 0, v1, v182 op_sel_hi:[0,0,0]
	s_setprio 0
	s_barrier
; #define PG8_STAGE(bufoff, gbase, voff) do { _Pragma("unroll") for (int _i = 0; _i < 2; ++_i) \
;         __builtin_amdgcn_global_load_lds((const unsigned*)((const char*)(gbase) + (voff)[_i]), (PG8_LAS unsigned*)(lds + (bufoff) + ldsw + _i * 8192), 16, 0, 0); } while (0)
; #define PG8_LDA(dst, b, h) do { _Pragma("unroll") for (int m = 0; m < 4; ++m) _Pragma("unroll") for (int k = 0; k < 2; ++k) dst[m][k] = *(const PG8_LAS bf16x8*)(lds + PG8_SA(b, h) + aoff + m * 2048 + k * 1024); } while (0)
; #define PG8_LDB(dst, b, h) do { _Pragma("unroll") for (int n = 0; n < 2; ++n) _Pragma("unroll") for (int k = 0; k < 2; ++k) dst[n][k] = *(const PG8_LAS bf16x8*)(lds + PG8_SB(b, h) + boff + n * 2048 + k * 1024); } while (0)
; #define PG8_BAR __builtin_amdgcn_s_barrier()
; template <class Epi, class Sched, bool ALIGN_EPI = false>
; __device__ __forceinline__ void gemm_phase8(PG8_LAS unsigned char* lds, const Gemm g, const Sched& S, const Epi& E) {
;     ...
;         for (int t = 0; t < nt; t += 2) {
;             const bool last = (t == nt - 2);
;             const char* a1 = cA + (size_t)(t + 1) * kstep;
;             const char* a2 = last ? nA : cA + (size_t)(t + 2) * kstep; const char* b2 = last ? nB : cB + (size_t)(t + 2) * kstep;
;             const char* a3 = a2 + kstep; const char* b3 = b2 + kstep;
;             if (last && has_next) S.a_ready(nxt);
;             PG8_LDB(B0, 0, 0); PG8_LDB(B1, 0, 1); PG8_SCHED; PG8_LDA(At, 0, 0); PG8_STAGE(PG8_SA(1, 1), a1 + hstepA, voffA);
;             PG8_WAIT_V(8); PG8_WAIT_L(0); PG8_BAR; PG8_MMA(0, 0, At, B0); PG8_MMA(0, 1, At, B1); PG8_BAR; PG8_SCHED;
;             PG8_LDA(At, 0, 1); PG8_STAGE(PG8_SB(0, 0), b2, voffB); PG8_STAGE(PG8_SB(0, 1), b2 + hstepB, voffB); PG8_STAGE(PG8_SA(0, 0), a2, voffA);
;             PG8_WAIT_V(8); PG8_WAIT_L(0); PG8_BAR; PG8_MMA(1, 0, At, B0); PG8_MMA(1, 1, At, B1); PG8_BAR; PG8_SCHED;
;             PG8_LDB(B0, 1, 0); PG8_LDB(B1, 1, 1); PG8_SCHED; PG8_LDA(At, 1, 0); PG8_STAGE(PG8_SA(0, 1), a2 + hstepA, voffA);
;             PG8_WAIT_V(8); PG8_WAIT_L(0); PG8_BAR; PG8_MMA(0, 0, At, B0); PG8_MMA(0, 1, At, B1); PG8_BAR; PG8_SCHED;
;             PG8_LDA(At, 1, 1); PG8_STAGE(PG8_SB(1, 0), b3, voffB); PG8_STAGE(PG8_SB(1, 1), b3 + hstepB, voffB); PG8_STAGE(PG8_SA(1, 0), a3, voffA);
;             PG8_WAIT_V(8); PG8_WAIT_L(0); PG8_BAR; PG8_MMA(1, 0, At, B0); PG8_MMA(1, 1, At, B1); PG8_BAR; PG8_SCHED;
	s_add_i32 s83, 0, 0x18000
	s_add_i32 s84, 0, 0x1c000
	v_add_u32_e32 v6, s83, v184
	v_add_u32_e32 v14, s83, v185
	v_add_u32_e32 v22, s84, v184
	v_add_u32_e32 v30, s84, v185
	ds_read_b128 v[2:5], v6
	ds_read_b128 v[10:13], v6 offset:2048
	ds_read_b128 v[6:9], v14
	ds_read_b128 v[14:17], v14 offset:2048
	ds_read_b128 v[18:21], v22
	ds_read_b128 v[26:29], v22 offset:2048
	ds_read_b128 v[22:25], v30
	ds_read_b128 v[30:33], v30 offset:2048
	s_add_u32 s40, s40, 0xb0000
	s_addc_u32 s41, s41, 0
	s_mov_b32 m0, s54
	ds_read_b128 v[194:197], v191 offset:32768
	ds_read_b128 v[202:205], v191 offset:34816
	ds_read_b128 v[198:201], v192 offset:32768
	ds_read_b128 v[206:209], v192 offset:34816
	ds_read_b128 v[210:213], v191 offset:36864
	ds_read_b128 v[218:221], v191 offset:38912
	ds_read_b128 v[214:217], v192 offset:36864
	ds_read_b128 v[222:225], v192 offset:38912
	global_load_lds_dwordx4 v162, s[40:41]
	s_mov_b32 m0, s55
	s_nop 0
	global_load_lds_dwordx4 v166, s[40:41]
	s_waitcnt vmcnt(8)
	s_waitcnt lgkmcnt(0)
	s_barrier
	s_setprio 1
	s_waitcnt lgkmcnt(0)
	v_mfma_scale_f32_16x16x128_f8f6f4 v[158:161], v[2:9], v[194:201], v[158:161], v1, v182 op_sel_hi:[0,0,0]
	v_mfma_scale_f32_16x16x128_f8f6f4 v[154:157], v[10:17], v[194:201], v[154:157], v1, v182 op_sel_hi:[0,0,0]
	v_mfma_scale_f32_16x16x128_f8f6f4 v[150:153], v[2:9], v[202:209], v[150:153], v1, v182 op_sel_hi:[0,0,0]
	v_mfma_scale_f32_16x16x128_f8f6f4 v[138:141], v[10:17], v[202:209], v[138:141], v1, v182 op_sel_hi:[0,0,0]
	v_mfma_scale_f32_16x16x128_f8f6f4 v[130:133], v[2:9], v[210:217], v[130:133], v1, v182 op_sel_hi:[0,0,0]
	v_mfma_scale_f32_16x16x128_f8f6f4 v[122:125], v[10:17], v[210:217], v[122:125], v1, v182 op_sel_hi:[0,0,0]
	v_mfma_scale_f32_16x16x128_f8f6f4 v[118:121], v[2:9], v[218:225], v[118:121], v1, v182 op_sel_hi:[0,0,0]
	v_mfma_scale_f32_16x16x128_f8f6f4 v[106:109], v[10:17], v[218:225], v[106:109], v1, v182 op_sel_hi:[0,0,0]
	s_setprio 0
	s_setprio 1
	v_mfma_scale_f32_16x16x128_f8f6f4 v[146:149], v[18:25], v[194:201], v[146:149], v1, v182 op_sel_hi:[0,0,0]
	v_mfma_scale_f32_16x16x128_f8f6f4 v[142:145], v[26:33], v[194:201], v[142:145], v1, v182 op_sel_hi:[0,0,0]
	v_mfma_scale_f32_16x16x128_f8f6f4 v[134:137], v[18:25], v[202:209], v[134:137], v1, v182 op_sel_hi:[0,0,0]
	v_mfma_scale_f32_16x16x128_f8f6f4 v[126:129], v[26:33], v[202:209], v[126:129], v1, v182 op_sel_hi:[0,0,0]
	v_mfma_scale_f32_16x16x128_f8f6f4 v[114:117], v[18:25], v[210:217], v[114:117], v1, v182 op_sel_hi:[0,0,0]
	v_mfma_scale_f32_16x16x128_f8f6f4 v[110:113], v[26:33], v[210:217], v[110:113], v1, v182 op_sel_hi:[0,0,0]
	v_mfma_scale_f32_16x16x128_f8f6f4 v[102:105], v[18:25], v[218:225], v[102:105], v1, v182 op_sel_hi:[0,0,0]
	v_mfma_scale_f32_16x16x128_f8f6f4 v[98:101], v[26:33], v[218:225], v[98:101], v1, v182 op_sel_hi:[0,0,0]
	s_setprio 0
	s_barrier
	s_add_i32 s101, s83, s45
	s_add_u32 s98, s34, s12
	s_addc_u32 s99, s35, s13
	s_mov_b32 m0, s101
	ds_read_b128 v[194:197], v191 offset:49152
	ds_read_b128 v[202:205], v191 offset:51200
	ds_read_b128 v[198:201], v192 offset:49152
	ds_read_b128 v[206:209], v192 offset:51200
	ds_read_b128 v[210:213], v191 offset:53248
	ds_read_b128 v[218:221], v191 offset:55296
	ds_read_b128 v[214:217], v192 offset:53248
	ds_read_b128 v[222:225], v192 offset:55296
	global_load_lds_dwordx4 v164, s[98:99]
	s_add_i32 m0, s101, 0x2000
	s_add_u32 s34, s34, 0xb0080
	s_addc_u32 s35, s35, 0
	s_add_i32 s101, s84, s45
	global_load_lds_dwordx4 v168, s[98:99]
	s_add_u32 s98, s40, s12
	s_addc_u32 s99, s41, s13
	s_sub_u32 s98, s98, 0xb0000
	s_subb_u32 s99, s99, 0
	s_mov_b32 m0, s101
	s_nop 0
	global_load_lds_dwordx4 v164, s[34:35]
	s_add_i32 m0, s101, 0x2000
	s_nop 0
	global_load_lds_dwordx4 v168, s[34:35]
	s_mov_b32 m0, s61
	s_nop 0
	global_load_lds_dwordx4 v162, s[98:99]
	s_mov_b32 m0, s62
	s_nop 0
	global_load_lds_dwordx4 v166, s[98:99]
	s_waitcnt vmcnt(8)
	s_waitcnt lgkmcnt(0)
	s_barrier
	s_setprio 1
	s_waitcnt lgkmcnt(0)
	v_mfma_scale_f32_16x16x128_f8f6f4 v[94:97], v[2:9], v[194:201], v[94:97], v1, v182 op_sel_hi:[0,0,0]
	v_mfma_scale_f32_16x16x128_f8f6f4 v[90:93], v[10:17], v[194:201], v[90:93], v1, v182 op_sel_hi:[0,0,0]
	v_mfma_scale_f32_16x16x128_f8f6f4 v[82:85], v[2:9], v[202:209], v[82:85], v1, v182 op_sel_hi:[0,0,0]
	v_mfma_scale_f32_16x16x128_f8f6f4 v[74:77], v[10:17], v[202:209], v[74:77], v1, v182 op_sel_hi:[0,0,0]
	v_mfma_scale_f32_16x16x128_f8f6f4 v[66:69], v[2:9], v[210:217], v[66:69], v1, v182 op_sel_hi:[0,0,0]
	v_mfma_scale_f32_16x16x128_f8f6f4 v[58:61], v[10:17], v[210:217], v[58:61], v1, v182 op_sel_hi:[0,0,0]
	v_mfma_scale_f32_16x16x128_f8f6f4 v[50:53], v[2:9], v[218:225], v[50:53], v1, v182 op_sel_hi:[0,0,0]
	v_mfma_scale_f32_16x16x128_f8f6f4 v[42:45], v[10:17], v[218:225], v[42:45], v1, v182 op_sel_hi:[0,0,0]
	s_setprio 0
	s_setprio 1
	v_mfma_scale_f32_16x16x128_f8f6f4 v[86:89], v[18:25], v[194:201], v[86:89], v1, v182 op_sel_hi:[0,0,0]
	v_mfma_scale_f32_16x16x128_f8f6f4 v[78:81], v[26:33], v[194:201], v[78:81], v1, v182 op_sel_hi:[0,0,0]
	v_mfma_scale_f32_16x16x128_f8f6f4 v[70:73], v[18:25], v[202:209], v[70:73], v1, v182 op_sel_hi:[0,0,0]
	v_mfma_scale_f32_16x16x128_f8f6f4 v[62:65], v[26:33], v[202:209], v[62:65], v1, v182 op_sel_hi:[0,0,0]
	v_mfma_scale_f32_16x16x128_f8f6f4 v[54:57], v[18:25], v[210:217], v[54:57], v1, v182 op_sel_hi:[0,0,0]
	v_mfma_scale_f32_16x16x128_f8f6f4 v[46:49], v[26:33], v[210:217], v[46:49], v1, v182 op_sel_hi:[0,0,0]
	v_mfma_scale_f32_16x16x128_f8f6f4 v[38:41], v[18:25], v[218:225], v[38:41], v1, v182 op_sel_hi:[0,0,0]
	v_mfma_scale_f32_16x16x128_f8f6f4 v[34:37], v[26:33], v[218:225], v[34:37], v1, v182 op_sel_hi:[0,0,0]
	s_setprio 0
	s_barrier
	s_add_u32 s38, s38, 0x100
	s_addc_u32 s39, s39, 0
	s_add_u32 s80, s80, 0x100
	s_addc_u32 s81, s81, 0
	s_cmp_ge_u32 s82, s31
	s_mov_b32 s40, s82
	.p2align	6
